# attention loop instruction trimming: merged LDS waits per MFMA pair, DMA offsets advanced in VGPRs with fixed SGPR bases, simpler loop counter/skip test, rescale branch on saved scalar mask, cold path
# baseline (speedup 1.0000x reference)
; DI void phase_attn(int wid0, const Params& p, int L, unsigned char* lds, bool dry) {
;     ...
;         const int qrow0 = meta ? MREG : b * 4096 + 128 * qb, qpos0 = meta ? 0 : 16 + 128 * qb, ntiles = meta ? 1 : 1 + 4 * (qb + 1);
;         if (tid < 130) tab[tid] = (tid < 129) ? biasT[hh * 129 + tid] : -__builtin_inff();
;         int myrow = qrow0 + 32 * rg + r32; if (meta && myrow > MREG + 63) myrow = MREG + 63;
;         const bf16_t* qp = qbuf + (size_t)myrow * 2048 + hh * 256 + psub * 128 + hi * 8;
;         unsigned char* qlds = lds + wid * 8192 + lane * 16;
; #pragma unroll
;         for (int d0 = 0; d0 < 8; ++d0) *(bf16x8*)(qlds + d0 * 1024) = *(const bf16x8*)(qp + d0 * 16);
;         const int wq0 = qpos0 + 32 * rg, qpos = wq0 + r32;
;         const float bfar = biasT[hh * 129 + 128];
;         const bf16_t* kh_ = kbuf + hh * 256; const bf16_t* vh_ = vbuf + hh * 256;
;         attn_stage(kh_ + (size_t)MREG * 2048, vh_ + (size_t)MREG * 2048, koff, voff, ldsl + 65536, wid);
;         f32x16 o[8];
; #pragma unroll
;         for (int d = 0; d < 8; ++d)
; #pragma unroll
;             for (int r = 0; r < 16; ++r) o[d][r] = 0.f;
;         float m_reg = -1e30f, l_reg = 0.f;
.LBB0_97:
	s_or_b64 exec, exec, s[10:11]
	s_lshl_b32 s40, s73, 12
	s_lshl_b32 s10, s75, 7
	s_add_i32 s9, s40, s10
	s_and_b64 s[6:7], s[76:77], exec
	s_cselect_b32 s71, 0x8000, s9
	s_lshl_b32 s6, s75, 2
	s_add_i32 s9, s6, 5
	s_and_b64 s[6:7], s[76:77], exec
	v_ashrrev_i32_e32 v0, 4, v4
	v_readlane_b32 s7, v245, 61
	v_and_b32_e32 v2, 15, v4
	v_lshrrev_b32_e32 v3, 1, v4
	v_add_u32_e32 v0, s7, v0
	v_bitop3_b32 v2, v0, v2, 15 bitop3:0x6c
	v_lshlrev_b32_e32 v0, 12, v0
	v_lshl_or_b32 v0, v2, 4, v0
	v_lshrrev_b32_e32 v2, 2, v4
	v_and_b32_e32 v3, 8, v3
	v_readlane_b32 s7, v245, 63
	v_and_or_b32 v2, v2, 3, v3
	v_lshlrev_b32_e32 v8, 3, v4
	v_add_u32_e32 v3, s7, v4
	v_readlane_b32 s7, v244, 1
	v_and_b32_e32 v7, 31, v4
	v_and_b32_e32 v3, 0xe0, v3
	v_and_b32_e32 v5, 24, v8
	v_lshl_add_u32 v2, v2, 11, s7
	v_or3_b32 v2, v2, v3, v5
	v_or_b32_e32 v3, s41, v7
	v_or_b32_e32 v3, s71, v3
	v_min_i32_e32 v9, 0x803f, v3
	v_cndmask_b32_e64 v10, v3, v9, s[76:77]
	s_cselect_b32 s6, 1, s9
	v_ashrrev_i32_e32 v11, 31, v10
	s_lshl_b32 s12, s49, 8
	v_lshlrev_b64 v[10:11], 12, v[10:11]
	s_ashr_i32 s13, s12, 31
	v_ashrrev_i32_e32 v6, 5, v4
	v_lshl_add_u64 v[10:11], s[0:1], 0, v[10:11]
	s_lshl_b64 s[78:79], s[12:13], 1
	v_readlane_b32 s12, v244, 5
	v_lshl_add_u64 v[10:11], v[10:11], 0, s[78:79]
	v_readlane_b32 s13, v244, 6
	v_lshlrev_b32_e32 v12, 3, v6
	v_ashrrev_i32_e32 v13, 31, v12
	v_lshl_add_u64 v[10:11], s[12:13], 1, v[10:11]
	v_lshl_add_u64 v[14:15], v[12:13], 1, v[10:11]
	global_load_dwordx4 v[248:251], v[14:15], off
	s_ashr_i32 s9, s8, 31
	s_lshl_b64 s[8:9], s[8:9], 2
	v_readlane_b32 s12, v245, 40
	v_lshlrev_b32_e32 v9, 4, v4
	v_readlane_b32 s7, v244, 7
	v_readlane_b32 s13, v245, 41
	s_add_u32 s8, s12, s8
	s_addc_u32 s9, s13, s9
	global_load_dword v176, v1, s[8:9] offset:512
	s_add_u32 s12, s28, s78
	s_addc_u32 s13, s29, s79
	s_mov_b64 s[84:85], s[12:13]
	v_readlane_b32 s8, v245, 38
	v_readlane_b32 s9, v245, 39
	s_add_u32 s8, s8, s78
	v_readlane_b32 s7, v244, 9
	s_addc_u32 s9, s9, s79
	s_mov_b64 s[86:87], s[8:9]
	v_lshl_add_u64 v[178:179], s[12:13], 0, v[0:1]
	v_mov_b32_e32 v131, v0
	s_mov_b64 s[14:15], 0x8000000
	s_add_i32 s7, s7, 0
	v_lshlrev_b32_e32 v2, 1, v2
	s_add_i32 m0, s7, 0x10000
	s_mov_b64 s[12:13], 0x8000100
	v_mov_b32_e32 v3, v1
	v_lshl_add_u64 v[180:181], s[8:9], 0, v[2:3]
	v_mov_b32_e32 v208, v2
	v_lshl_add_u64 v[2:3], v[180:181], 0, s[14:15]
	s_mov_b64 s[8:9], 0x8010000
	global_load_dwordx4 v[252:255], v[14:15], off offset:32
	global_load_dwordx4 v[200:203], v[14:15], off offset:64
	global_load_dwordx4 v[204:207], v[14:15], off offset:96
	global_load_dwordx4 v[164:167], v[14:15], off offset:128
	global_load_dwordx4 v[168:171], v[14:15], off offset:160
	global_load_dwordx4 v[172:175], v[14:15], off offset:192
	global_load_dwordx4 v[232:235], v[14:15], off offset:224
	v_lshl_add_u64 v[10:11], v[178:179], 0, s[14:15]
	global_load_lds_dwordx4 v[10:11], off
	v_lshl_add_u64 v[10:11], v[178:179], 0, s[12:13]
	s_add_i32 m0, s7, 0x12000
	s_nop 0
	global_load_lds_dwordx4 v[10:11], off
	s_add_i32 m0, s7, 0x0
	s_nop 0
	global_load_lds_dwordx4 v[2:3], off
	v_lshl_add_u64 v[2:3], v[180:181], 0, s[8:9]
	s_add_i32 m0, s7, 0x2000
	s_mov_b32 s7, 0
	global_load_lds_dwordx4 v[2:3], off
	s_cmp_lt_i32 s6, 1
	s_cbranch_scc1 .LBB0_114
	s_or_b32 s10, s10, 16
	v_lshlrev_b32_e32 v0, 8, v7
	v_bitop3_b32 v2, v6, v4, 1 bitop3:0x78
	s_and_b64 s[8:9], s[76:77], exec
	v_lshl_add_u32 v193, v2, 4, v0
	v_lshlrev_b32_e32 v2, 1, v4
	s_cselect_b32 s39, 0, s10
	v_and_b32_e32 v0, 0xc0, v9
	v_and_b32_e32 v2, 32, v2
	v_readlane_b32 s48, v244, 17
	s_or_b32 s8, s39, s41
	v_and_b32_e32 v3, 0x100, v8
	v_add3_u32 v0, s48, v0, v2
	v_mov_b32_e32 v14, v1
	v_mov_b32_e32 v15, v1
	s_add_i32 s38, s8, 31
	v_and_b32_e32 v192, 0xe0, v9
	v_lshlrev_b32_e32 v194, 2, v6
	v_add_u32_e32 v195, s8, v7
	v_cmp_gt_u32_e64 s[8:9], 32, v4
	v_lshl_add_u32 v196, v7, 2, s2
	v_lshlrev_b32_e32 v16, 4, v6
	v_cmp_gt_i32_e64 s[10:11], 4, v6
	v_cmp_gt_i32_e64 s[18:19], 2, v6
	v_cmp_gt_i32_e64 s[20:21], 0, v6
	v_cmp_gt_i32_e64 s[22:23], -2, v6
	v_add3_u32 v212, v0, v3, v5
	v_add_u32_e32 v212, 0xffff0000, v212
	v_mov_b32_e32 v0, v1
	v_mov_b32_e32 v2, v1
	v_mov_b32_e32 v3, v1
	v_mov_b32_e32 v4, v1
	v_mov_b32_e32 v5, v1
	v_mov_b32_e32 v6, v1
	v_mov_b32_e32 v7, v1
	v_mov_b32_e32 v8, v1
	v_mov_b32_e32 v9, v1
	v_mov_b32_e32 v10, v1
	v_mov_b32_e32 v11, v1
	v_mov_b32_e32 v12, v1
	v_mov_b32_e32 v13, v1
	v_mov_b64_e32 v[128:129], v[14:15]
	v_mov_b64_e32 v[112:113], v[14:15]
	v_mov_b64_e32 v[96:97], v[14:15]
	v_mov_b64_e32 v[80:81], v[14:15]
	v_mov_b64_e32 v[64:65], v[14:15]
	v_mov_b64_e32 v[48:49], v[14:15]
	v_mov_b64_e32 v[32:33], v[14:15]
	v_or_b32_e32 v197, 1, v194
	v_or_b32_e32 v198, 2, v194
	v_or_b32_e32 v199, 3, v194
	v_readlane_b32 s48, v244, 19
	v_add_u32_e32 v214, s2, v16
	v_mov_b64_e32 v[126:127], v[12:13]
	v_mov_b64_e32 v[124:125], v[10:11]
	v_mov_b64_e32 v[122:123], v[8:9]
	v_mov_b64_e32 v[120:121], v[6:7]
	v_mov_b64_e32 v[118:119], v[4:5]
	v_mov_b64_e32 v[116:117], v[2:3]
	v_mov_b64_e32 v[114:115], v[0:1]
	v_mov_b64_e32 v[110:111], v[12:13]
	v_mov_b64_e32 v[108:109], v[10:11]
	v_mov_b64_e32 v[106:107], v[8:9]
	v_mov_b64_e32 v[104:105], v[6:7]
	v_mov_b64_e32 v[102:103], v[4:5]
	v_mov_b64_e32 v[100:101], v[2:3]
	v_mov_b64_e32 v[98:99], v[0:1]
	v_mov_b64_e32 v[94:95], v[12:13]
	v_mov_b64_e32 v[92:93], v[10:11]
	v_mov_b64_e32 v[90:91], v[8:9]
	v_mov_b64_e32 v[88:89], v[6:7]
	v_mov_b64_e32 v[86:87], v[4:5]
	v_mov_b64_e32 v[84:85], v[2:3]
	v_mov_b64_e32 v[82:83], v[0:1]
	v_mov_b64_e32 v[78:79], v[12:13]
	v_mov_b64_e32 v[76:77], v[10:11]
	v_mov_b64_e32 v[74:75], v[8:9]
	v_mov_b64_e32 v[72:73], v[6:7]
	v_mov_b64_e32 v[70:71], v[4:5]
	v_mov_b64_e32 v[68:69], v[2:3]
	v_mov_b64_e32 v[66:67], v[0:1]
	v_mov_b64_e32 v[62:63], v[12:13]
	v_mov_b64_e32 v[60:61], v[10:11]
	v_mov_b64_e32 v[58:59], v[8:9]
	v_mov_b64_e32 v[56:57], v[6:7]
	v_mov_b64_e32 v[54:55], v[4:5]
	v_mov_b64_e32 v[52:53], v[2:3]
	v_mov_b64_e32 v[50:51], v[0:1]
	v_mov_b64_e32 v[46:47], v[12:13]
	v_mov_b64_e32 v[44:45], v[10:11]
	v_mov_b64_e32 v[42:43], v[8:9]
	v_mov_b64_e32 v[40:41], v[6:7]
	v_mov_b64_e32 v[38:39], v[4:5]
	v_mov_b64_e32 v[36:37], v[2:3]
	v_mov_b64_e32 v[34:35], v[0:1]
	v_mov_b64_e32 v[30:31], v[12:13]
	v_mov_b64_e32 v[28:29], v[10:11]
	v_mov_b64_e32 v[26:27], v[8:9]
	v_mov_b64_e32 v[24:25], v[6:7]
	v_mov_b64_e32 v[22:23], v[4:5]
	v_mov_b64_e32 v[20:21], v[2:3]
	v_mov_b64_e32 v[18:19], v[0:1]
	v_mov_b64_e32 v[16:17], v[14:15]
	v_cmp_gt_i32_e64 s[12:13], 16, v197
	v_cmp_gt_i32_e64 s[14:15], 16, v198
	v_cmp_gt_i32_e64 s[16:17], 16, v199
	s_waitcnt vmcnt(11)
; #define MFMA32(a, b, c) __builtin_amdgcn_mfma_f32_32x32x16_bf16((a), (b), (c), 0, 0, 0)
; DI void phase_attn(int wid0, const Params& p, int L, unsigned char* lds, bool dry) {
;     ...
;         for (int t = 0; t < ntiles; ++t) {
;             asm volatile("s_waitcnt vmcnt(0) lgkmcnt(0)" ::: "memory"); __builtin_amdgcn_s_barrier(); asm volatile("" ::: "memory");
;             if (t + 1 < ntiles) attn_stage(kh_ + (size_t)(b * 4096 + 32 * t) * 2048, vh_ + (size_t)(b * 4096 + 32 * t) * 2048, koff, voff, ldsl + 65536 + ((t + 1) & 1) * 32768, wid);
;             const int kpos0 = (t == 0) ? 0 : 16 + 32 * (t - 1);
;             if (kpos0 <= wq0 + 31) {
;                 const unsigned char* Ks = lds + 65536 + (t & 1) * 32768 + psub * 8192;
;                 f32x16 p0, p0b;
; #pragma unroll
;                 for (int r = 0; r < 16; ++r) { p0[r] = 0.f; p0b[r] = 0.f; }
;                 int swz = (r32 & 6) << 4, kro = r32 * 256 + ((hi ^ (r32 & 1)) << 4); asm volatile("" : "+v"(swz), "+v"(kro));
; #pragma unroll
;                 for (int d0 = 0; d0 < 8; d0 += 2) {
;                     const bf16x8 b0 = *(const bf16x8*)(Ks + kro + ((d0 * 32) ^ swz));
;                     const bf16x8 qf = *(const bf16x8*)(qlds + d0 * 1024);
;                     const bf16x8 b1 = *(const bf16x8*)(Ks + kro + (((d0 + 1) * 32) ^ swz));
;                     const bf16x8 qg = *(const bf16x8*)(qlds + (d0 + 1) * 1024);
;                     p0 = MFMA32(b0, qf, p0);
;                     p0b = MFMA32(b1, qg, p0b);
;                     if (d0 == 2) __builtin_amdgcn_sched_barrier(0);
;                 }
; #pragma unroll
;                 for (int r = 0; r < 16; ++r) p0[r] += p0b[r];
;                 __builtin_amdgcn_sched_barrier(0);
;                 if (t > 0 && wq0 - (kpos0 + 31) >= 128) {
; #pragma unroll
;                     for (int r = 0; r < 16; ++r) p0[r] = fmaf(p0[r], ATT_C, bfar);
	v_mov_b32_e32 v182, v176
	v_mov_b32_e32 v183, v176
	s_add_i32 s39, s48, s39
	v_mov_b32_e32 v130, 0
	v_mov_b32_e32 v213, 0xf149f2ca
	s_mov_b32 s66, 0
	s_mov_b32 s100, 0x100
	s_mov_b32 s67, 1
	s_mov_b32 s7, -16
	s_mov_b32 s97, 0x4138aa3b
	s_mov_b32 s80, s40
	s_mov_b32 s81, 0
	s_lshl_b64 s[80:81], s[80:81], 12
	s_add_u32 s88, s84, s80
	s_addc_u32 s89, s85, s81
	s_add_u32 s92, s86, s80
	s_addc_u32 s93, s87, s81
	s_add_u32 s94, s92, 0x10000
	s_addc_u32 s95, s93, 0
	s_add_u32 s90, s88, 0x100
	s_addc_u32 s91, s89, 0
	s_add_i32 s96, s4, 0xffff0000
	v_mov_b32_e32 v132, 0
	v_mov_b32_e32 v133, 0
	v_mov_b32_e32 v134, 0
	v_mov_b32_e32 v135, 0
	v_mov_b32_e32 v136, 0
	v_mov_b32_e32 v137, 0
	v_mov_b32_e32 v138, 0
	v_mov_b32_e32 v139, 0
	s_lshl_b32 s80, s96, 1
	s_add_i32 s80, s80, 0xc000
	v_lshl_add_u32 v226, v190, 4, s80
	ds_write_b128 v226, v[132:135]
	ds_write_b128 v226, v[132:135] offset:1024
	v_add_u32_e32 v226, s5, v193
	v_add_u32_e32 v188, v226, v192
	v_xad_u32 v177, v192, 32, v226
	v_xad_u32 v209, v192, 64, v226
	s_movk_i32 s80, 0x60
	v_xad_u32 v210, v192, s80, v226
	s_movk_i32 s80, 0x80
	v_xad_u32 v211, v192, s80, v226
	s_movk_i32 s80, 0xa0
	v_xad_u32 v215, v192, s80, v226
	s_movk_i32 s80, 0xc0
	v_xad_u32 v224, v192, s80, v226
	s_movk_i32 s80, 0xe0
	v_xad_u32 v225, v192, s80, v226
	v_mov_b64_e32 v[14:15], v[12:13]
	v_mov_b64_e32 v[12:13], v[10:11]
	v_mov_b64_e32 v[10:11], v[8:9]
	v_mov_b64_e32 v[8:9], v[6:7]
	v_mov_b64_e32 v[6:7], v[4:5]
	v_mov_b64_e32 v[4:5], v[2:3]
	v_mov_b64_e32 v[2:3], v[0:1]
	s_mov_b32 s69, 0
.LBB0_99:
	s_waitcnt vmcnt(0) lgkmcnt(0)
	s_barrier
	s_cmp_ge_i32 s67, s6
	s_cbranch_scc1 .Lattn_nodma0
	s_add_i32 m0, s4, 0x8000
	s_nop 0
	global_load_lds_dwordx4 v131, s[88:89]
	s_add_i32 m0, s4, 0xa000
	s_nop 0
	global_load_lds_dwordx4 v131, s[90:91]
	s_add_i32 m0, s96, 0x4000
	v_add_u32_e32 v131, 0x20000, v131
	global_load_lds_dwordx4 v208, s[92:93]
	s_add_i32 m0, s96, 0x6000
	s_nop 0
	global_load_lds_dwordx4 v208, s[94:95]
	v_add_u32_e32 v208, 0x20000, v208
.Lattn_nodma0:
	s_max_i32 s48, s7, 0
	s_cmp_gt_i32 s48, s38
	s_cbranch_scc1 .Lattn_skip0
	ds_read_b128 v[216:219], v188
	ds_read_b128 v[220:223], v177
	ds_read_b128 v[236:239], v209
	ds_read_b128 v[240:243], v210
	s_waitcnt lgkmcnt(2)
	v_mfma_f32_32x32x16_bf16 v[140:155], v[216:219], v[248:251], 0
	v_mfma_f32_32x32x16_bf16 v[140:155], v[220:223], v[252:255], v[140:155]
	ds_read_b128 v[216:219], v211
	ds_read_b128 v[220:223], v215
	s_waitcnt lgkmcnt(2)
	v_mfma_f32_32x32x16_bf16 v[140:155], v[236:239], v[200:203], v[140:155]
	v_mfma_f32_32x32x16_bf16 v[140:155], v[240:243], v[204:207], v[140:155]
	ds_read_b128 v[236:239], v224
	ds_read_b128 v[240:243], v225
	s_waitcnt lgkmcnt(2)
	v_mfma_f32_32x32x16_bf16 v[140:155], v[216:219], v[164:167], v[140:155]
	v_mfma_f32_32x32x16_bf16 v[140:155], v[220:223], v[168:171], v[140:155]
	s_waitcnt lgkmcnt(0)
	v_mfma_f32_32x32x16_bf16 v[140:155], v[236:239], v[172:175], v[140:155]
	v_mfma_f32_32x32x16_bf16 v[140:155], v[240:243], v[232:235], v[140:155]
	s_cmpk_gt_i32 s39, 0x7f
	s_cbranch_scc0 .Lattn_near0
	s_cmp_lg_u32 s67, 1
	s_cbranch_scc1 .Lattn_far0
; DI int crow(int r, int hi) { return (r & 3) + 8 * (r >> 2) + 4 * hi; }
; DI void phase_attn(int wid0, const Params& p, int L, unsigned char* lds, bool dry) {
;     ...
;                 } else {
; #pragma unroll
;                     for (int r = 0; r < 16; ++r) {
;                         const int k0i = crow(r, hi);
;                         const int d0v = qpos - (kpos0 + k0i);
;                         const bool v0 = (d0v >= 0) && (t > 0 || k0i < 16);
;                         const int idx = v0 ? (d0v < 128 ? d0v : 128) : 129;
;                         p0[r] = fmaf(p0[r], ATT_C, tab[idx]);
;                         if ((r & 3) == 3) __builtin_amdgcn_sched_barrier(0);
;                     }
;                 }
.Lattn_near0:
	s_cmp_lg_u32 s67, 1
	s_cselect_b64 s[80:81], -1, 0
	v_add_u32_e32 v226, s48, v194
	v_sub_u32_e32 v229, v195, v226
	v_sub_u32_e32 v216, v195, v226
	v_cmp_lt_i32_e32 vcc, -1, v216
	s_or_b64 s[82:83], s[10:11], s[80:81]
	v_add_u32_e32 v217, s48, v197
	v_min_i32_e32 v216, 0x80, v216
	s_and_b64 vcc, s[82:83], vcc
	v_sub_u32_e32 v217, v195, v217
	v_cndmask_b32_e32 v216, v187, v216, vcc
	v_cmp_lt_i32_e32 vcc, -1, v217
	s_or_b64 s[82:83], s[12:13], s[80:81]
	v_add_u32_e32 v218, s48, v198
	v_min_i32_e32 v217, 0x80, v217
	s_and_b64 vcc, s[82:83], vcc
	v_sub_u32_e32 v218, v195, v218
	v_cndmask_b32_e32 v217, v187, v217, vcc
	v_cmp_lt_i32_e32 vcc, -1, v218
	s_or_b64 s[82:83], s[14:15], s[80:81]
	v_add_u32_e32 v219, s48, v199
	v_min_i32_e32 v218, 0x80, v218
	s_and_b64 vcc, s[82:83], vcc
	v_sub_u32_e32 v219, v195, v219
	v_cndmask_b32_e32 v218, v187, v218, vcc
	v_cmp_lt_i32_e32 vcc, -1, v219
	s_or_b64 s[82:83], s[16:17], s[80:81]
	v_min_i32_e32 v219, 0x80, v219
	s_and_b64 vcc, s[82:83], vcc
	v_cndmask_b32_e32 v219, v187, v219, vcc
	v_lshl_add_u32 v216, v216, 2, s37
	v_lshl_add_u32 v217, v217, 2, s37
	v_lshl_add_u32 v218, v218, 2, s37
	v_lshl_add_u32 v219, v219, 2, s37
	ds_read_b32 v216, v216
	ds_read_b32 v217, v217
	ds_read_b32 v218, v218
	ds_read_b32 v219, v219
	v_add_u32_e32 v220, -8, v229
	v_cmp_lt_i32_e32 vcc, -1, v220
	s_or_b64 s[82:83], s[18:19], s[80:81]
	v_min_i32_e32 v220, 0x80, v220
	s_and_b64 vcc, s[82:83], vcc
	v_add_u32_e32 v221, -9, v229
	v_cndmask_b32_e32 v220, v187, v220, vcc
	v_cmp_lt_i32_e32 vcc, -1, v221
	v_min_i32_e32 v221, 0x80, v221
	s_and_b64 vcc, s[82:83], vcc
	v_add_u32_e32 v222, -10, v229
	v_cndmask_b32_e32 v221, v187, v221, vcc
	v_cmp_lt_i32_e32 vcc, -1, v222
	v_min_i32_e32 v222, 0x80, v222
	s_and_b64 vcc, s[82:83], vcc
	v_add_u32_e32 v223, -11, v229
	v_cndmask_b32_e32 v222, v187, v222, vcc
	v_cmp_lt_i32_e32 vcc, -1, v223
	v_min_i32_e32 v223, 0x80, v223
	s_and_b64 vcc, s[82:83], vcc
	v_cndmask_b32_e32 v223, v187, v223, vcc
	v_lshl_add_u32 v220, v220, 2, s37
	v_lshl_add_u32 v221, v221, 2, s37
	v_lshl_add_u32 v222, v222, 2, s37
	v_lshl_add_u32 v223, v223, 2, s37
	ds_read_b32 v220, v220
	ds_read_b32 v221, v221
	ds_read_b32 v222, v222
	ds_read_b32 v223, v223
	v_add_u32_e32 v236, -16, v229
	v_cmp_lt_i32_e32 vcc, -1, v236
	s_or_b64 s[82:83], s[20:21], s[80:81]
	v_min_i32_e32 v236, 0x80, v236
	s_and_b64 vcc, s[82:83], vcc
	v_add_u32_e32 v237, 0xffffffef, v229
	v_cndmask_b32_e32 v236, v187, v236, vcc
	v_cmp_lt_i32_e32 vcc, -1, v237
	v_min_i32_e32 v237, 0x80, v237
	s_and_b64 vcc, s[82:83], vcc
	v_add_u32_e32 v238, 0xffffffee, v229
	v_cndmask_b32_e32 v237, v187, v237, vcc
	v_cmp_lt_i32_e32 vcc, -1, v238
	v_min_i32_e32 v238, 0x80, v238
	s_and_b64 vcc, s[82:83], vcc
	v_add_u32_e32 v239, 0xffffffed, v229
	v_cndmask_b32_e32 v238, v187, v238, vcc
	v_cmp_lt_i32_e32 vcc, -1, v239
	v_min_i32_e32 v239, 0x80, v239
	s_and_b64 vcc, s[82:83], vcc
	v_cndmask_b32_e32 v239, v187, v239, vcc
	v_lshl_add_u32 v236, v236, 2, s37
	v_lshl_add_u32 v237, v237, 2, s37
	v_lshl_add_u32 v238, v238, 2, s37
	v_lshl_add_u32 v239, v239, 2, s37
	ds_read_b32 v236, v236
	ds_read_b32 v237, v237
	ds_read_b32 v238, v238
	ds_read_b32 v239, v239
	v_add_u32_e32 v240, 0xffffffe8, v229
	v_cmp_lt_i32_e32 vcc, -1, v240
	s_or_b64 s[80:81], s[22:23], s[80:81]
	v_min_i32_e32 v240, 0x80, v240
	s_and_b64 vcc, s[80:81], vcc
	v_add_u32_e32 v241, 0xffffffe7, v229
	v_cndmask_b32_e32 v240, v187, v240, vcc
	v_cmp_lt_i32_e32 vcc, -1, v241
	v_min_i32_e32 v241, 0x80, v241
	s_and_b64 vcc, s[80:81], vcc
	v_add_u32_e32 v242, 0xffffffe6, v229
	v_cndmask_b32_e32 v241, v187, v241, vcc
	v_cmp_lt_i32_e32 vcc, -1, v242
	v_min_i32_e32 v242, 0x80, v242
	s_and_b64 vcc, s[80:81], vcc
	v_add_u32_e32 v226, 0xffffffe5, v229
	v_cndmask_b32_e32 v242, v187, v242, vcc
	v_cmp_lt_i32_e32 vcc, -1, v226
	v_min_i32_e32 v226, 0x80, v226
	s_and_b64 vcc, s[80:81], vcc
	v_lshl_add_u32 v240, v240, 2, s37
	v_lshl_add_u32 v241, v241, 2, s37
	v_lshl_add_u32 v242, v242, 2, s37
	v_cndmask_b32_e32 v226, v187, v226, vcc
	v_lshl_add_u32 v226, v226, 2, s37
	ds_read_b32 v240, v240
	ds_read_b32 v241, v241
	ds_read_b32 v242, v242
	ds_read_b32 v243, v226
	s_waitcnt lgkmcnt(0)
	v_pk_fma_f32 v[140:141], v[140:141], s[36:37], v[216:217] op_sel_hi:[1,0,1]
	v_pk_fma_f32 v[142:143], v[142:143], s[36:37], v[218:219] op_sel_hi:[1,0,1]
	v_pk_fma_f32 v[144:145], v[144:145], s[36:37], v[220:221] op_sel_hi:[1,0,1]
	v_pk_fma_f32 v[146:147], v[146:147], s[36:37], v[222:223] op_sel_hi:[1,0,1]
	v_pk_fma_f32 v[148:149], v[148:149], s[36:37], v[236:237] op_sel_hi:[1,0,1]
	v_pk_fma_f32 v[150:151], v[150:151], s[36:37], v[238:239] op_sel_hi:[1,0,1]
	v_pk_fma_f32 v[152:153], v[152:153], s[36:37], v[240:241] op_sel_hi:[1,0,1]
	v_pk_fma_f32 v[154:155], v[154:155], s[36:37], v[242:243] op_sel_hi:[1,0,1]
	s_mov_b32 s82, 1.0
	v_mov_b32_e32 v231, 0
	s_branch .Lattn_region0

; DI void phase_attn(int wid0, const Params& p, int L, unsigned char* lds, bool dry) {
;     ...
;                 float pmax = p0[0];
; #pragma unroll
;                 for (int r = 1; r < 16; ++r) pmax = fmaxf(pmax, p0[r]);
;                 { auto rr = __builtin_amdgcn_permlane32_swap(__float_as_uint(pmax), __float_as_uint(pmax), false, false); pmax = fmaxf(__uint_as_float(rr[0]), __uint_as_float(rr[1])); }
;                 float mn, alpha;
;                 if (__all(pmax - m_reg <= ATT_THR2)) { mn = m_reg; alpha = 1.f; }
;                 else { mn = fmaxf(m_reg, pmax); alpha = __builtin_amdgcn_exp2f(m_reg - mn); m_reg = mn; }
;                 float ps = 0.f;
; #pragma unroll
;                 for (int r = 0; r < 16; ++r) { p0[r] = __builtin_amdgcn_exp2f(p0[r] - mn); ps += p0[r]; }
;                 { auto rr = __builtin_amdgcn_permlane32_swap(__float_as_uint(ps), __float_as_uint(ps), false, false); ps = __uint_as_float(rr[0]) + __uint_as_float(rr[1]); }
;                 l_reg = l_reg * alpha + ps;
;                 __builtin_amdgcn_sched_barrier(0);
;                 bf16x8 pa0, pa1;
;     ...
;                 PK4(p0, 0, pa0); PK4(p0, 8, pa1);
;     ...
;                 __builtin_amdgcn_sched_barrier(0);
;                 if (__any(alpha < 1.f)) {
;                     if (hi == 0) al_l[r32] = alpha;
;                     asm volatile("s_waitcnt lgkmcnt(0)" ::: "memory");
;                     float ar[16];
; #pragma unroll
;                     for (int r = 0; r < 16; ++r) ar[r] = al_l[crow(r, hi)];
; #pragma unroll
;                     for (int d = 0; d < 8; ++d)
; #pragma unroll
;                         for (int r = 0; r < 16; ++r) o[d][r] *= ar[r];
;                 }
;                 __builtin_amdgcn_sched_barrier(0);
;                 LAS unsigned char* vbp = ldsl + 65536 + (t & 1) * 32768 + 16384 + v_rd_base(lane);
;                 __builtin_amdgcn_s_setprio(1);
;     ...
;                 {
;                     s16x4 a0, a1, a2, a3, b0_, b1_, b2_, b3_;
;                     PV_RD(0, a0, a1, a2, a3); SB();
;                     PV_RD(1, b0_, b1_, b2_, b3_); SB(); PV_MM(0, a0, a1, a2, a3); SB();
;                     PV_RD(2, a0, a1, a2, a3); SB(); PV_MM(1, b0_, b1_, b2_, b3_); SB();
;                     PV_RD(3, b0_, b1_, b2_, b3_); SB(); PV_MM(2, a0, a1, a2, a3); SB();
;                     PV_RD(4, a0, a1, a2, a3); SB(); PV_MM(3, b0_, b1_, b2_, b3_); SB();
.Lattn_region0:
	ds_read_b64_tr_b16 v[216:217], v212 offset:49152
	ds_read_b64_tr_b16 v[218:219], v212 offset:53248
	ds_read_b64_tr_b16 v[220:221], v212 offset:57344
	ds_read_b64_tr_b16 v[222:223], v212 offset:61440
	ds_read_b64_tr_b16 v[236:237], v212 offset:49664
	ds_read_b64_tr_b16 v[238:239], v212 offset:53760
	ds_read_b64_tr_b16 v[240:241], v212 offset:57856
	ds_read_b64_tr_b16 v[242:243], v212 offset:61952
	s_waitcnt lgkmcnt(4)
	v_mfma_f32_32x32x16_bf16 v[114:129], v[132:135], v[216:219], v[114:129]
	v_mfma_f32_32x32x16_bf16 v[114:129], v[136:139], v[220:223], v[114:129]
	v_max3_f32 v226, v140, v141, v142
	v_max3_f32 v226, v226, v143, v144
	v_max3_f32 v226, v226, v145, v146
	v_max3_f32 v226, v226, v147, v148
	v_max3_f32 v226, v226, v149, v150
	v_max3_f32 v226, v226, v151, v152
	v_max3_f32 v226, v226, v153, v154
	ds_read_b64_tr_b16 v[216:217], v212 offset:50176
	ds_read_b64_tr_b16 v[218:219], v212 offset:54272
	ds_read_b64_tr_b16 v[220:221], v212 offset:58368
	ds_read_b64_tr_b16 v[222:223], v212 offset:62464
	s_waitcnt lgkmcnt(4)
	v_mfma_f32_32x32x16_bf16 v[98:113], v[132:135], v[236:239], v[98:113]
	v_max_f32_e32 v226, v226, v155
	v_mov_b32_e32 v227, v226
	s_nop 1
	v_permlane32_swap_b32_e32 v226, v227
	v_max_f32_e32 v226, v226, v227
	v_fma_f32 v226, v226, s82, v231
	v_sub_f32_e32 v227, v226, v213
	v_cmp_ge_f32_e32 vcc, s97, v227
	v_mfma_f32_32x32x16_bf16 v[98:113], v[136:139], v[240:243], v[98:113]
	s_cmp_eq_u64 vcc, exec
	v_max_f32_e32 v226, v213, v226
	s_cselect_b64 vcc, -1, 0
	v_sub_f32_e32 v227, v213, v226
	v_cndmask_b32_e32 v213, v226, v213, vcc
	v_sub_f32_e32 v230, v231, v213
	v_fma_f32 v140, v140, s82, v230
	v_exp_f32_e32 v140, v140
	ds_read_b64_tr_b16 v[236:237], v212 offset:50688
	ds_read_b64_tr_b16 v[238:239], v212 offset:54784
	ds_read_b64_tr_b16 v[240:241], v212 offset:58880
	ds_read_b64_tr_b16 v[242:243], v212 offset:62976
	s_waitcnt lgkmcnt(4)
	v_mfma_f32_32x32x16_bf16 v[82:97], v[132:135], v[216:219], v[82:97]
	v_fma_f32 v141, v141, s82, v230
	v_exp_f32_e32 v141, v141
	v_fma_f32 v142, v142, s82, v230
	v_exp_f32_e32 v142, v142
	v_add_f32_e32 v226, v140, v141
	v_mfma_f32_32x32x16_bf16 v[82:97], v[136:139], v[220:223], v[82:97]
	v_fma_f32 v143, v143, s82, v230
	v_exp_f32_e32 v143, v143
	v_add_f32_e32 v226, v226, v142
	v_fma_f32 v144, v144, s82, v230
	v_exp_f32_e32 v144, v144
	ds_read_b64_tr_b16 v[216:217], v212 offset:51200
	ds_read_b64_tr_b16 v[218:219], v212 offset:55296
	ds_read_b64_tr_b16 v[220:221], v212 offset:59392
	ds_read_b64_tr_b16 v[222:223], v212 offset:63488
	s_waitcnt lgkmcnt(4)
	v_mfma_f32_32x32x16_bf16 v[66:81], v[132:135], v[236:239], v[66:81]
	v_add_f32_e32 v226, v226, v143
	v_fma_f32 v145, v145, s82, v230
	v_exp_f32_e32 v145, v145
	v_add_f32_e32 v226, v226, v144
	v_fma_f32 v146, v146, s82, v230
	v_exp_f32_e32 v146, v146
	v_mfma_f32_32x32x16_bf16 v[66:81], v[136:139], v[240:243], v[66:81]
	v_add_f32_e32 v226, v226, v145
	v_fma_f32 v147, v147, s82, v230
	v_exp_f32_e32 v147, v147
	v_add_f32_e32 v226, v226, v146
	v_fma_f32 v148, v148, s82, v230
	v_exp_f32_e32 v148, v148
	ds_read_b64_tr_b16 v[236:237], v212 offset:51712
	ds_read_b64_tr_b16 v[238:239], v212 offset:55808
	ds_read_b64_tr_b16 v[240:241], v212 offset:59904
	ds_read_b64_tr_b16 v[242:243], v212 offset:64000
	s_waitcnt lgkmcnt(4)
	v_mfma_f32_32x32x16_bf16 v[50:65], v[132:135], v[216:219], v[50:65]
	v_add_f32_e32 v226, v226, v147
	v_fma_f32 v149, v149, s82, v230
	v_exp_f32_e32 v149, v149
	v_add_f32_e32 v226, v226, v148
	v_fma_f32 v150, v150, s82, v230
	v_exp_f32_e32 v150, v150
	v_mfma_f32_32x32x16_bf16 v[50:65], v[136:139], v[220:223], v[50:65]
	v_add_f32_e32 v226, v226, v149
	v_fma_f32 v151, v151, s82, v230
	v_exp_f32_e32 v151, v151
	v_add_f32_e32 v226, v226, v150
	v_fma_f32 v152, v152, s82, v230
	ds_read_b64_tr_b16 v[216:217], v212 offset:52224
	ds_read_b64_tr_b16 v[218:219], v212 offset:56320
	ds_read_b64_tr_b16 v[220:221], v212 offset:60416
	ds_read_b64_tr_b16 v[222:223], v212 offset:64512
	s_waitcnt lgkmcnt(4)
	v_mfma_f32_32x32x16_bf16 v[34:49], v[132:135], v[236:239], v[34:49]
	v_exp_f32_e32 v152, v152
	v_add_f32_e32 v226, v226, v151
	v_fma_f32 v153, v153, s82, v230
	v_exp_f32_e32 v153, v153
	v_mfma_f32_32x32x16_bf16 v[34:49], v[136:139], v[240:243], v[34:49]
	v_add_f32_e32 v226, v226, v152
	v_fma_f32 v154, v154, s82, v230
	v_exp_f32_e32 v154, v154
	v_add_f32_e32 v226, v226, v153
	v_fma_f32 v155, v155, s82, v230
	ds_read_b64_tr_b16 v[236:237], v212 offset:52736
	ds_read_b64_tr_b16 v[238:239], v212 offset:56832
	ds_read_b64_tr_b16 v[240:241], v212 offset:60928
	ds_read_b64_tr_b16 v[242:243], v212 offset:65024
	s_waitcnt lgkmcnt(4)
	v_mfma_f32_32x32x16_bf16 v[18:33], v[132:135], v[216:219], v[18:33]
	v_exp_f32_e32 v155, v155
	v_add_f32_e32 v226, v226, v154
	v_exp_f32_e32 v227, v227
	v_add_f32_e32 v228, v226, v155
	v_mfma_f32_32x32x16_bf16 v[18:33], v[136:139], v[220:223], v[18:33]
	v_cndmask_b32_e64 v227, v227, 1.0, vcc
	v_mov_b32_e32 v229, v228
	v_cvt_pk_bf16_f32 v156, v140, v141
	v_cvt_pk_bf16_f32 v157, v142, v143
	v_cvt_pk_bf16_f32 v158, v144, v145
	v_cvt_pk_bf16_f32 v159, v146, v147
	s_waitcnt lgkmcnt(0)
	v_mfma_f32_32x32x16_bf16 v[2:17], v[132:135], v[236:239], v[2:17]
	v_cvt_pk_bf16_f32 v160, v148, v149
	v_cvt_pk_bf16_f32 v161, v150, v151
	v_cvt_pk_bf16_f32 v162, v152, v153
	v_cvt_pk_bf16_f32 v163, v154, v155
	v_permlane32_swap_b32_e32 v228, v229
	v_permlane32_swap_b32_e32 v156, v158
	v_mfma_f32_32x32x16_bf16 v[2:17], v[136:139], v[240:243], v[2:17]
	v_permlane32_swap_b32_e32 v157, v159
	v_permlane32_swap_b32_e32 v160, v162
	v_permlane32_swap_b32_e32 v161, v163
	v_add_f32_e32 v228, v228, v229
	v_fma_f32 v130, v130, v227, v228
	s_cbranch_vccnz .Lattn_norescale0
; DI int crow(int r, int hi) { return (r & 3) + 8 * (r >> 2) + 4 * hi; }
; #define MFMA32(a, b, c) __builtin_amdgcn_mfma_f32_32x32x16_bf16((a), (b), (c), 0, 0, 0)
; DI void phase_attn(int wid0, const Params& p, int L, unsigned char* lds, bool dry) {
;     ...
;         for (int t = 0; t < ntiles; ++t) {
;             asm volatile("s_waitcnt vmcnt(0) lgkmcnt(0)" ::: "memory"); __builtin_amdgcn_s_barrier(); asm volatile("" ::: "memory");
;             if (t + 1 < ntiles) attn_stage(kh_ + (size_t)(b * 4096 + 32 * t) * 2048, vh_ + (size_t)(b * 4096 + 32 * t) * 2048, koff, voff, ldsl + 65536 + ((t + 1) & 1) * 32768, wid);
;             const int kpos0 = (t == 0) ? 0 : 16 + 32 * (t - 1);
;             if (kpos0 <= wq0 + 31) {
;                 const unsigned char* Ks = lds + 65536 + (t & 1) * 32768 + psub * 8192;
;                 f32x16 p0, p0b;
; #pragma unroll
;                 for (int r = 0; r < 16; ++r) { p0[r] = 0.f; p0b[r] = 0.f; }
;                 int swz = (r32 & 6) << 4, kro = r32 * 256 + ((hi ^ (r32 & 1)) << 4); asm volatile("" : "+v"(swz), "+v"(kro));
; #pragma unroll
;                 for (int d0 = 0; d0 < 8; d0 += 2) {
;                     const bf16x8 b0 = *(const bf16x8*)(Ks + kro + ((d0 * 32) ^ swz));
;                     const bf16x8 qf = *(const bf16x8*)(qlds + d0 * 1024);
;                     const bf16x8 b1 = *(const bf16x8*)(Ks + kro + (((d0 + 1) * 32) ^ swz));
;                     const bf16x8 qg = *(const bf16x8*)(qlds + (d0 + 1) * 1024);
;                     p0 = MFMA32(b0, qf, p0);
;                     p0b = MFMA32(b1, qg, p0b);
;                     if (d0 == 2) __builtin_amdgcn_sched_barrier(0);
;                 }
; #pragma unroll
;                 for (int r = 0; r < 16; ++r) p0[r] += p0b[r];
;                 __builtin_amdgcn_sched_barrier(0);
;     ...
;                 if (__any(alpha < 1.f)) {
;                     if (hi == 0) al_l[r32] = alpha;
;                     asm volatile("s_waitcnt lgkmcnt(0)" ::: "memory");
;                     float ar[16];
; #pragma unroll
;                     for (int r = 0; r < 16; ++r) ar[r] = al_l[crow(r, hi)];
; #pragma unroll
;                     for (int d = 0; d < 8; ++d)
; #pragma unroll
;                         for (int r = 0; r < 16; ++r) o[d][r] *= ar[r];
;                 }
	s_and_saveexec_b64 s[80:81], s[8:9]
	ds_write_b32 v196, v227 offset:128
	s_or_b64 exec, exec, s[80:81]
	s_waitcnt lgkmcnt(0)
	ds_read_b128 v[152:155], v214 offset:224
	ds_read_b128 v[148:151], v214 offset:192
	ds_read_b128 v[144:147], v214 offset:160
	ds_read_b128 v[140:143], v214 offset:128
	s_waitcnt lgkmcnt(0)
	v_pk_mul_f32 v[126:127], v[126:127], v[152:153]
	v_pk_mul_f32 v[122:123], v[122:123], v[148:149]
	v_pk_mul_f32 v[118:119], v[118:119], v[144:145]
	v_pk_mul_f32 v[128:129], v[128:129], v[154:155]
	v_pk_mul_f32 v[124:125], v[124:125], v[150:151]
	v_pk_mul_f32 v[120:121], v[120:121], v[146:147]
	v_pk_mul_f32 v[116:117], v[116:117], v[142:143]
	v_pk_mul_f32 v[114:115], v[114:115], v[140:141]
	v_pk_mul_f32 v[110:111], v[110:111], v[152:153]
	v_pk_mul_f32 v[106:107], v[106:107], v[148:149]
	v_pk_mul_f32 v[102:103], v[102:103], v[144:145]
	v_pk_mul_f32 v[112:113], v[112:113], v[154:155]
	v_pk_mul_f32 v[108:109], v[108:109], v[150:151]
	v_pk_mul_f32 v[104:105], v[104:105], v[146:147]
	v_pk_mul_f32 v[100:101], v[100:101], v[142:143]
	v_pk_mul_f32 v[98:99], v[98:99], v[140:141]
	v_pk_mul_f32 v[94:95], v[94:95], v[152:153]
	v_pk_mul_f32 v[90:91], v[90:91], v[148:149]
	v_pk_mul_f32 v[86:87], v[86:87], v[144:145]
	v_pk_mul_f32 v[96:97], v[96:97], v[154:155]
	v_pk_mul_f32 v[92:93], v[92:93], v[150:151]
	v_pk_mul_f32 v[88:89], v[88:89], v[146:147]
	v_pk_mul_f32 v[84:85], v[84:85], v[142:143]
	v_pk_mul_f32 v[82:83], v[82:83], v[140:141]
	v_pk_mul_f32 v[78:79], v[78:79], v[152:153]
	v_pk_mul_f32 v[74:75], v[74:75], v[148:149]
	v_pk_mul_f32 v[70:71], v[70:71], v[144:145]
	v_pk_mul_f32 v[80:81], v[80:81], v[154:155]
	v_pk_mul_f32 v[76:77], v[76:77], v[150:151]
	v_pk_mul_f32 v[72:73], v[72:73], v[146:147]
	v_pk_mul_f32 v[68:69], v[68:69], v[142:143]
	v_pk_mul_f32 v[66:67], v[66:67], v[140:141]
	v_pk_mul_f32 v[62:63], v[62:63], v[152:153]
	v_pk_mul_f32 v[58:59], v[58:59], v[148:149]
	v_pk_mul_f32 v[54:55], v[54:55], v[144:145]
	v_pk_mul_f32 v[64:65], v[64:65], v[154:155]
	v_pk_mul_f32 v[60:61], v[60:61], v[150:151]
	v_pk_mul_f32 v[56:57], v[56:57], v[146:147]
	v_pk_mul_f32 v[52:53], v[52:53], v[142:143]
	v_pk_mul_f32 v[50:51], v[50:51], v[140:141]
	v_pk_mul_f32 v[46:47], v[46:47], v[152:153]
	v_pk_mul_f32 v[42:43], v[42:43], v[148:149]
	v_pk_mul_f32 v[38:39], v[38:39], v[144:145]
	v_pk_mul_f32 v[48:49], v[48:49], v[154:155]
	v_pk_mul_f32 v[44:45], v[44:45], v[150:151]
	v_pk_mul_f32 v[40:41], v[40:41], v[146:147]
	v_pk_mul_f32 v[36:37], v[36:37], v[142:143]
	v_pk_mul_f32 v[34:35], v[34:35], v[140:141]
	v_pk_mul_f32 v[30:31], v[30:31], v[152:153]
	v_pk_mul_f32 v[26:27], v[26:27], v[148:149]
	v_pk_mul_f32 v[22:23], v[22:23], v[144:145]
	v_pk_mul_f32 v[32:33], v[32:33], v[154:155]
	v_pk_mul_f32 v[28:29], v[28:29], v[150:151]
	v_pk_mul_f32 v[24:25], v[24:25], v[146:147]
	v_pk_mul_f32 v[20:21], v[20:21], v[142:143]
	v_pk_mul_f32 v[18:19], v[18:19], v[140:141]
	v_pk_mul_f32 v[14:15], v[14:15], v[152:153]
	v_pk_mul_f32 v[10:11], v[10:11], v[148:149]
	v_pk_mul_f32 v[6:7], v[6:7], v[144:145]
	v_pk_mul_f32 v[16:17], v[16:17], v[154:155]
	v_pk_mul_f32 v[12:13], v[12:13], v[150:151]
	v_pk_mul_f32 v[8:9], v[8:9], v[146:147]
	v_pk_mul_f32 v[4:5], v[4:5], v[142:143]
	v_pk_mul_f32 v[2:3], v[2:3], v[140:141]
.Lattn_norescale0:
.Lattn_latch0:
	s_sub_i32 s39, s39, 32
	s_add_i32 s7, s7, 32
	s_cmp_eq_u32 s6, s67
	s_cbranch_scc1 .Lattn_exit0
	s_add_i32 s67, s67, 1
.Lattn_top1:
	s_waitcnt vmcnt(0) lgkmcnt(0)
	s_barrier
	s_cmp_ge_i32 s67, s6
	s_cbranch_scc1 .Lattn_nodma1
	s_add_i32 m0, s4, 0x0
	s_nop 0
	global_load_lds_dwordx4 v131, s[88:89]
	s_add_i32 m0, s4, 0x2000
	s_nop 0
	global_load_lds_dwordx4 v131, s[90:91]
	s_add_i32 m0, s96, 0x8000
	v_add_u32_e32 v131, 0x20000, v131
	global_load_lds_dwordx4 v208, s[92:93]
	s_add_i32 m0, s96, 0xa000
	s_nop 0
	global_load_lds_dwordx4 v208, s[94:95]
	v_add_u32_e32 v208, 0x20000, v208
.Lattn_nodma1:
	s_max_i32 s48, s7, 0
	s_cmp_gt_i32 s48, s38
	s_cbranch_scc1 .Lattn_skip1
	ds_read_b128 v[216:219], v188 offset:32768
	ds_read_b128 v[220:223], v177 offset:32768
	ds_read_b128 v[236:239], v209 offset:32768
	ds_read_b128 v[240:243], v210 offset:32768
	s_waitcnt lgkmcnt(2)
	v_mfma_f32_32x32x16_bf16 v[140:155], v[216:219], v[248:251], 0
	v_mfma_f32_32x32x16_bf16 v[140:155], v[220:223], v[252:255], v[140:155]
	ds_read_b128 v[216:219], v211 offset:32768
	ds_read_b128 v[220:223], v215 offset:32768
	s_waitcnt lgkmcnt(2)
	v_mfma_f32_32x32x16_bf16 v[140:155], v[236:239], v[200:203], v[140:155]
	v_mfma_f32_32x32x16_bf16 v[140:155], v[240:243], v[204:207], v[140:155]
	ds_read_b128 v[236:239], v224 offset:32768
	ds_read_b128 v[240:243], v225 offset:32768
	s_waitcnt lgkmcnt(2)
	v_mfma_f32_32x32x16_bf16 v[140:155], v[216:219], v[164:167], v[140:155]
	v_mfma_f32_32x32x16_bf16 v[140:155], v[220:223], v[168:171], v[140:155]
	s_waitcnt lgkmcnt(0)
	v_mfma_f32_32x32x16_bf16 v[140:155], v[236:239], v[172:175], v[140:155]
	v_mfma_f32_32x32x16_bf16 v[140:155], v[240:243], v[232:235], v[140:155]
	s_cmpk_gt_i32 s39, 0x7f
	s_cbranch_scc0 .Lattn_near1
	s_cmp_lg_u32 s67, 1
	s_cbranch_scc1 .Lattn_far1

; DI void phase_attn(int wid0, const Params& p, int L, unsigned char* lds, bool dry) {
;     ...
;                 float pmax = p0[0];
; #pragma unroll
;                 for (int r = 1; r < 16; ++r) pmax = fmaxf(pmax, p0[r]);
;                 { auto rr = __builtin_amdgcn_permlane32_swap(__float_as_uint(pmax), __float_as_uint(pmax), false, false); pmax = fmaxf(__uint_as_float(rr[0]), __uint_as_float(rr[1])); }
;                 float mn, alpha;
;                 if (__all(pmax - m_reg <= ATT_THR2)) { mn = m_reg; alpha = 1.f; }
;                 else { mn = fmaxf(m_reg, pmax); alpha = __builtin_amdgcn_exp2f(m_reg - mn); m_reg = mn; }
;                 float ps = 0.f;
; #pragma unroll
;                 for (int r = 0; r < 16; ++r) { p0[r] = __builtin_amdgcn_exp2f(p0[r] - mn); ps += p0[r]; }
;                 { auto rr = __builtin_amdgcn_permlane32_swap(__float_as_uint(ps), __float_as_uint(ps), false, false); ps = __uint_as_float(rr[0]) + __uint_as_float(rr[1]); }
;                 l_reg = l_reg * alpha + ps;
;                 __builtin_amdgcn_sched_barrier(0);
;                 bf16x8 pa0, pa1;
;     ...
;                 PK4(p0, 0, pa0); PK4(p0, 8, pa1);
;     ...
;                 __builtin_amdgcn_sched_barrier(0);
;                 if (__any(alpha < 1.f)) {
;                     if (hi == 0) al_l[r32] = alpha;
;                     asm volatile("s_waitcnt lgkmcnt(0)" ::: "memory");
;                     float ar[16];
; #pragma unroll
;                     for (int r = 0; r < 16; ++r) ar[r] = al_l[crow(r, hi)];
; #pragma unroll
;                     for (int d = 0; d < 8; ++d)
; #pragma unroll
;                         for (int r = 0; r < 16; ++r) o[d][r] *= ar[r];
;                 }
;                 __builtin_amdgcn_sched_barrier(0);
;                 LAS unsigned char* vbp = ldsl + 65536 + (t & 1) * 32768 + 16384 + v_rd_base(lane);
;                 __builtin_amdgcn_s_setprio(1);
;     ...
;                 {
;                     s16x4 a0, a1, a2, a3, b0_, b1_, b2_, b3_;
;                     PV_RD(0, a0, a1, a2, a3); SB();
;                     PV_RD(1, b0_, b1_, b2_, b3_); SB(); PV_MM(0, a0, a1, a2, a3); SB();
;                     PV_RD(2, a0, a1, a2, a3); SB(); PV_MM(1, b0_, b1_, b2_, b3_); SB();
;                     PV_RD(3, b0_, b1_, b2_, b3_); SB(); PV_MM(2, a0, a1, a2, a3); SB();
;                     PV_RD(4, a0, a1, a2, a3); SB(); PV_MM(3, b0_, b1_, b2_, b3_); SB();
.Lattn_region1:
	ds_read_b64_tr_b16 v[216:217], v212 offset:0
	ds_read_b64_tr_b16 v[218:219], v212 offset:4096
	ds_read_b64_tr_b16 v[220:221], v212 offset:8192
	ds_read_b64_tr_b16 v[222:223], v212 offset:12288
	ds_read_b64_tr_b16 v[236:237], v212 offset:512
	ds_read_b64_tr_b16 v[238:239], v212 offset:4608
	ds_read_b64_tr_b16 v[240:241], v212 offset:8704
	ds_read_b64_tr_b16 v[242:243], v212 offset:12800
	s_waitcnt lgkmcnt(4)
	v_mfma_f32_32x32x16_bf16 v[114:129], v[156:159], v[216:219], v[114:129]
	v_mfma_f32_32x32x16_bf16 v[114:129], v[160:163], v[220:223], v[114:129]
	v_max3_f32 v226, v140, v141, v142
	v_max3_f32 v226, v226, v143, v144
	v_max3_f32 v226, v226, v145, v146
	v_max3_f32 v226, v226, v147, v148
	v_max3_f32 v226, v226, v149, v150
	v_max3_f32 v226, v226, v151, v152
	v_max3_f32 v226, v226, v153, v154
	ds_read_b64_tr_b16 v[216:217], v212 offset:1024
	ds_read_b64_tr_b16 v[218:219], v212 offset:5120
	ds_read_b64_tr_b16 v[220:221], v212 offset:9216
	ds_read_b64_tr_b16 v[222:223], v212 offset:13312
	s_waitcnt lgkmcnt(4)
	v_mfma_f32_32x32x16_bf16 v[98:113], v[156:159], v[236:239], v[98:113]
	v_max_f32_e32 v226, v226, v155
	v_mov_b32_e32 v227, v226
	s_nop 1
	v_permlane32_swap_b32_e32 v226, v227
	v_max_f32_e32 v226, v226, v227
	v_fma_f32 v226, v226, s82, v231
	v_sub_f32_e32 v227, v226, v213
	v_cmp_ge_f32_e32 vcc, s97, v227
	v_mfma_f32_32x32x16_bf16 v[98:113], v[160:163], v[240:243], v[98:113]
	s_cmp_eq_u64 vcc, exec
	v_max_f32_e32 v226, v213, v226
	s_cselect_b64 vcc, -1, 0
	v_sub_f32_e32 v227, v213, v226
	v_cndmask_b32_e32 v213, v226, v213, vcc
	v_sub_f32_e32 v230, v231, v213
	v_fma_f32 v140, v140, s82, v230
	v_exp_f32_e32 v140, v140
	ds_read_b64_tr_b16 v[236:237], v212 offset:1536
	ds_read_b64_tr_b16 v[238:239], v212 offset:5632
	ds_read_b64_tr_b16 v[240:241], v212 offset:9728
	ds_read_b64_tr_b16 v[242:243], v212 offset:13824
	s_waitcnt lgkmcnt(4)
	v_mfma_f32_32x32x16_bf16 v[82:97], v[156:159], v[216:219], v[82:97]
	v_fma_f32 v141, v141, s82, v230
	v_exp_f32_e32 v141, v141
	v_fma_f32 v142, v142, s82, v230
	v_exp_f32_e32 v142, v142
	v_add_f32_e32 v226, v140, v141
	v_mfma_f32_32x32x16_bf16 v[82:97], v[160:163], v[220:223], v[82:97]
	v_fma_f32 v143, v143, s82, v230
	v_exp_f32_e32 v143, v143
	v_add_f32_e32 v226, v226, v142
	v_fma_f32 v144, v144, s82, v230
	v_exp_f32_e32 v144, v144
	ds_read_b64_tr_b16 v[216:217], v212 offset:2048
	ds_read_b64_tr_b16 v[218:219], v212 offset:6144
	ds_read_b64_tr_b16 v[220:221], v212 offset:10240
	ds_read_b64_tr_b16 v[222:223], v212 offset:14336
	s_waitcnt lgkmcnt(4)
	v_mfma_f32_32x32x16_bf16 v[66:81], v[156:159], v[236:239], v[66:81]
	v_add_f32_e32 v226, v226, v143
	v_fma_f32 v145, v145, s82, v230
	v_exp_f32_e32 v145, v145
	v_add_f32_e32 v226, v226, v144
	v_fma_f32 v146, v146, s82, v230
	v_exp_f32_e32 v146, v146
	v_mfma_f32_32x32x16_bf16 v[66:81], v[160:163], v[240:243], v[66:81]
	v_add_f32_e32 v226, v226, v145
	v_fma_f32 v147, v147, s82, v230
	v_exp_f32_e32 v147, v147
	v_add_f32_e32 v226, v226, v146
	v_fma_f32 v148, v148, s82, v230
	v_exp_f32_e32 v148, v148
	ds_read_b64_tr_b16 v[236:237], v212 offset:2560
	ds_read_b64_tr_b16 v[238:239], v212 offset:6656
	ds_read_b64_tr_b16 v[240:241], v212 offset:10752
	ds_read_b64_tr_b16 v[242:243], v212 offset:14848
	s_waitcnt lgkmcnt(4)
	v_mfma_f32_32x32x16_bf16 v[50:65], v[156:159], v[216:219], v[50:65]
	v_add_f32_e32 v226, v226, v147
	v_fma_f32 v149, v149, s82, v230
	v_exp_f32_e32 v149, v149
	v_add_f32_e32 v226, v226, v148
	v_fma_f32 v150, v150, s82, v230
	v_exp_f32_e32 v150, v150
	v_mfma_f32_32x32x16_bf16 v[50:65], v[160:163], v[220:223], v[50:65]
	v_add_f32_e32 v226, v226, v149
	v_fma_f32 v151, v151, s82, v230
	v_exp_f32_e32 v151, v151
	v_add_f32_e32 v226, v226, v150
	v_fma_f32 v152, v152, s82, v230
	ds_read_b64_tr_b16 v[216:217], v212 offset:3072
	ds_read_b64_tr_b16 v[218:219], v212 offset:7168
	ds_read_b64_tr_b16 v[220:221], v212 offset:11264
	ds_read_b64_tr_b16 v[222:223], v212 offset:15360
	s_waitcnt lgkmcnt(4)
	v_mfma_f32_32x32x16_bf16 v[34:49], v[156:159], v[236:239], v[34:49]
	v_exp_f32_e32 v152, v152
	v_add_f32_e32 v226, v226, v151
	v_fma_f32 v153, v153, s82, v230
	v_exp_f32_e32 v153, v153
	v_mfma_f32_32x32x16_bf16 v[34:49], v[160:163], v[240:243], v[34:49]
	v_add_f32_e32 v226, v226, v152
	v_fma_f32 v154, v154, s82, v230
	v_exp_f32_e32 v154, v154
	v_add_f32_e32 v226, v226, v153
	v_fma_f32 v155, v155, s82, v230
	ds_read_b64_tr_b16 v[236:237], v212 offset:3584
	ds_read_b64_tr_b16 v[238:239], v212 offset:7680
	ds_read_b64_tr_b16 v[240:241], v212 offset:11776
	ds_read_b64_tr_b16 v[242:243], v212 offset:15872
	s_waitcnt lgkmcnt(4)
	v_mfma_f32_32x32x16_bf16 v[18:33], v[156:159], v[216:219], v[18:33]
	v_exp_f32_e32 v155, v155
	v_add_f32_e32 v226, v226, v154
	v_exp_f32_e32 v227, v227
	v_add_f32_e32 v228, v226, v155
	v_mfma_f32_32x32x16_bf16 v[18:33], v[160:163], v[220:223], v[18:33]
	v_cndmask_b32_e64 v227, v227, 1.0, vcc
	v_mov_b32_e32 v229, v228
	v_cvt_pk_bf16_f32 v132, v140, v141
	v_cvt_pk_bf16_f32 v133, v142, v143
	v_cvt_pk_bf16_f32 v134, v144, v145
	v_cvt_pk_bf16_f32 v135, v146, v147
	s_waitcnt lgkmcnt(0)
	v_mfma_f32_32x32x16_bf16 v[2:17], v[156:159], v[236:239], v[2:17]
	v_cvt_pk_bf16_f32 v136, v148, v149
	v_cvt_pk_bf16_f32 v137, v150, v151
	v_cvt_pk_bf16_f32 v138, v152, v153
	v_cvt_pk_bf16_f32 v139, v154, v155
	v_permlane32_swap_b32_e32 v228, v229
	v_permlane32_swap_b32_e32 v132, v134
	v_mfma_f32_32x32x16_bf16 v[2:17], v[160:163], v[240:243], v[2:17]
	v_permlane32_swap_b32_e32 v133, v135
	v_permlane32_swap_b32_e32 v136, v138
	v_permlane32_swap_b32_e32 v137, v139
	v_add_f32_e32 v228, v228, v229
	v_fma_f32 v130, v130, v227, v228
	s_cbranch_vccnz .Lattn_norescale1
; DI int crow(int r, int hi) { return (r & 3) + 8 * (r >> 2) + 4 * hi; }
; DI void phase_attn(int wid0, const Params& p, int L, unsigned char* lds, bool dry) {
;     ...
;                 if (__any(alpha < 1.f)) {
;                     if (hi == 0) al_l[r32] = alpha;
;                     asm volatile("s_waitcnt lgkmcnt(0)" ::: "memory");
;                     float ar[16];
; #pragma unroll
;                     for (int r = 0; r < 16; ++r) ar[r] = al_l[crow(r, hi)];
; #pragma unroll
;                     for (int d = 0; d < 8; ++d)
; #pragma unroll
;                         for (int r = 0; r < 16; ++r) o[d][r] *= ar[r];
;                 }
	s_and_saveexec_b64 s[80:81], s[8:9]
	ds_write_b32 v196, v227 offset:128
	s_or_b64 exec, exec, s[80:81]
	s_waitcnt lgkmcnt(0)
	ds_read_b128 v[152:155], v214 offset:224
	ds_read_b128 v[148:151], v214 offset:192
	ds_read_b128 v[144:147], v214 offset:160
	ds_read_b128 v[140:143], v214 offset:128
	s_waitcnt lgkmcnt(0)
	v_pk_mul_f32 v[126:127], v[126:127], v[152:153]
	v_pk_mul_f32 v[122:123], v[122:123], v[148:149]
	v_pk_mul_f32 v[118:119], v[118:119], v[144:145]
	v_pk_mul_f32 v[128:129], v[128:129], v[154:155]
	v_pk_mul_f32 v[124:125], v[124:125], v[150:151]
	v_pk_mul_f32 v[120:121], v[120:121], v[146:147]
	v_pk_mul_f32 v[116:117], v[116:117], v[142:143]
	v_pk_mul_f32 v[114:115], v[114:115], v[140:141]
	v_pk_mul_f32 v[110:111], v[110:111], v[152:153]
	v_pk_mul_f32 v[106:107], v[106:107], v[148:149]
	v_pk_mul_f32 v[102:103], v[102:103], v[144:145]
	v_pk_mul_f32 v[112:113], v[112:113], v[154:155]
	v_pk_mul_f32 v[108:109], v[108:109], v[150:151]
	v_pk_mul_f32 v[104:105], v[104:105], v[146:147]
	v_pk_mul_f32 v[100:101], v[100:101], v[142:143]
	v_pk_mul_f32 v[98:99], v[98:99], v[140:141]
	v_pk_mul_f32 v[94:95], v[94:95], v[152:153]
	v_pk_mul_f32 v[90:91], v[90:91], v[148:149]
	v_pk_mul_f32 v[86:87], v[86:87], v[144:145]
	v_pk_mul_f32 v[96:97], v[96:97], v[154:155]
	v_pk_mul_f32 v[92:93], v[92:93], v[150:151]
	v_pk_mul_f32 v[88:89], v[88:89], v[146:147]
	v_pk_mul_f32 v[84:85], v[84:85], v[142:143]
	v_pk_mul_f32 v[82:83], v[82:83], v[140:141]
	v_pk_mul_f32 v[78:79], v[78:79], v[152:153]
	v_pk_mul_f32 v[74:75], v[74:75], v[148:149]
	v_pk_mul_f32 v[70:71], v[70:71], v[144:145]
	v_pk_mul_f32 v[80:81], v[80:81], v[154:155]
	v_pk_mul_f32 v[76:77], v[76:77], v[150:151]
	v_pk_mul_f32 v[72:73], v[72:73], v[146:147]
	v_pk_mul_f32 v[68:69], v[68:69], v[142:143]
	v_pk_mul_f32 v[66:67], v[66:67], v[140:141]
	v_pk_mul_f32 v[62:63], v[62:63], v[152:153]
	v_pk_mul_f32 v[58:59], v[58:59], v[148:149]
	v_pk_mul_f32 v[54:55], v[54:55], v[144:145]
	v_pk_mul_f32 v[64:65], v[64:65], v[154:155]
	v_pk_mul_f32 v[60:61], v[60:61], v[150:151]
	v_pk_mul_f32 v[56:57], v[56:57], v[146:147]
	v_pk_mul_f32 v[52:53], v[52:53], v[142:143]
	v_pk_mul_f32 v[50:51], v[50:51], v[140:141]
	v_pk_mul_f32 v[46:47], v[46:47], v[152:153]
	v_pk_mul_f32 v[42:43], v[42:43], v[148:149]
	v_pk_mul_f32 v[38:39], v[38:39], v[144:145]
	v_pk_mul_f32 v[48:49], v[48:49], v[154:155]
	v_pk_mul_f32 v[44:45], v[44:45], v[150:151]
	v_pk_mul_f32 v[40:41], v[40:41], v[146:147]
	v_pk_mul_f32 v[36:37], v[36:37], v[142:143]
	v_pk_mul_f32 v[34:35], v[34:35], v[140:141]
	v_pk_mul_f32 v[30:31], v[30:31], v[152:153]
	v_pk_mul_f32 v[26:27], v[26:27], v[148:149]
	v_pk_mul_f32 v[22:23], v[22:23], v[144:145]
	v_pk_mul_f32 v[32:33], v[32:33], v[154:155]
	v_pk_mul_f32 v[28:29], v[28:29], v[150:151]
	v_pk_mul_f32 v[24:25], v[24:25], v[146:147]
	v_pk_mul_f32 v[20:21], v[20:21], v[142:143]
	v_pk_mul_f32 v[18:19], v[18:19], v[140:141]
	v_pk_mul_f32 v[14:15], v[14:15], v[152:153]
	v_pk_mul_f32 v[10:11], v[10:11], v[148:149]
	v_pk_mul_f32 v[6:7], v[6:7], v[144:145]
	v_pk_mul_f32 v[16:17], v[16:17], v[154:155]
	v_pk_mul_f32 v[12:13], v[12:13], v[150:151]
	v_pk_mul_f32 v[8:9], v[8:9], v[146:147]
	v_pk_mul_f32 v[4:5], v[4:5], v[142:143]
	v_pk_mul_f32 v[2:3], v[2:3], v[140:141]

; #define LAS __attribute__((address_space(3)))
; DI void attn_stage(const bf16_t* kbase, const bf16_t* vbase, unsigned koff, unsigned voff, LAS unsigned char* ldsbuf, int wid) {
; #pragma unroll
;     for (int i = 0; i < 2; ++i) {
;         const char* src = (const char*)kbase + (size_t)(i * 128) * 2;
;         __builtin_amdgcn_global_load_lds((const unsigned*)(src + koff), (LAS unsigned*)(ldsbuf + (wid + 8 * i) * 1024), 16, 0, 0);
;     }
; #pragma unroll
;     for (int i = 0; i < 2; ++i) {
;         const char* src = (const char*)vbase + (size_t)(16 * i * 2048) * 2;
;         __builtin_amdgcn_global_load_lds((const unsigned*)(src + voff), (LAS unsigned*)(ldsbuf + 16384 + (wid + 8 * i) * 1024), 16, 0, 0);
;     }
; }
; DI void phase_attn(int wid0, const Params& p, int L, unsigned char* lds, bool dry) {
;     ...
;             asm volatile("s_waitcnt vmcnt(0) lgkmcnt(0)" ::: "memory"); __builtin_amdgcn_s_barrier(); asm volatile("" ::: "memory");
;             if (t + 1 < ntiles) attn_stage(kh_ + (size_t)(b * 4096 + 32 * t) * 2048, vh_ + (size_t)(b * 4096 + 32 * t) * 2048, koff, voff, ldsl + 65536 + ((t + 1) & 1) * 32768, wid);
;             const int kpos0 = (t == 0) ? 0 : 16 + 32 * (t - 1);
.Lattn_top2:
	s_waitcnt vmcnt(0) lgkmcnt(0)
	s_barrier
	s_cmp_ge_i32 s67, s6
	s_cbranch_scc1 .Lattn_nodma2
	s_add_i32 m0, s4, 0x8000
	s_nop 0
	global_load_lds_dwordx4 v131, s[88:89]
	s_add_i32 m0, s4, 0xa000
	s_nop 0
	global_load_lds_dwordx4 v131, s[90:91]
	s_add_i32 m0, s96, 0xc000
	v_add_u32_e32 v131, 0x20000, v131
	global_load_lds_dwordx4 v208, s[92:93]
	s_add_i32 m0, s96, 0xe000
	s_nop 0
	global_load_lds_dwordx4 v208, s[94:95]
	v_add_u32_e32 v208, 0x20000, v208

; DI void phase_attn(int wid0, const Params& p, int L, unsigned char* lds, bool dry) {
;     ...
;                 float pmax = p0[0];
; #pragma unroll
;                 for (int r = 1; r < 16; ++r) pmax = fmaxf(pmax, p0[r]);
;                 { auto rr = __builtin_amdgcn_permlane32_swap(__float_as_uint(pmax), __float_as_uint(pmax), false, false); pmax = fmaxf(__uint_as_float(rr[0]), __uint_as_float(rr[1])); }
;                 float mn, alpha;
;                 if (__all(pmax - m_reg <= ATT_THR2)) { mn = m_reg; alpha = 1.f; }
;                 else { mn = fmaxf(m_reg, pmax); alpha = __builtin_amdgcn_exp2f(m_reg - mn); m_reg = mn; }
;                 float ps = 0.f;
; #pragma unroll
;                 for (int r = 0; r < 16; ++r) { p0[r] = __builtin_amdgcn_exp2f(p0[r] - mn); ps += p0[r]; }
;                 { auto rr = __builtin_amdgcn_permlane32_swap(__float_as_uint(ps), __float_as_uint(ps), false, false); ps = __uint_as_float(rr[0]) + __uint_as_float(rr[1]); }
;                 l_reg = l_reg * alpha + ps;
;                 __builtin_amdgcn_sched_barrier(0);
;                 bf16x8 pa0, pa1;
;     ...
;                 PK4(p0, 0, pa0); PK4(p0, 8, pa1);
;     ...
;                 __builtin_amdgcn_sched_barrier(0);
;                 if (__any(alpha < 1.f)) {
;                     if (hi == 0) al_l[r32] = alpha;
;                     asm volatile("s_waitcnt lgkmcnt(0)" ::: "memory");
;                     float ar[16];
; #pragma unroll
;                     for (int r = 0; r < 16; ++r) ar[r] = al_l[crow(r, hi)];
; #pragma unroll
;                     for (int d = 0; d < 8; ++d)
; #pragma unroll
;                         for (int r = 0; r < 16; ++r) o[d][r] *= ar[r];
;                 }
;                 __builtin_amdgcn_sched_barrier(0);
;                 LAS unsigned char* vbp = ldsl + 65536 + (t & 1) * 32768 + 16384 + v_rd_base(lane);
;                 __builtin_amdgcn_s_setprio(1);
;     ...
;                 {
;                     s16x4 a0, a1, a2, a3, b0_, b1_, b2_, b3_;
;                     PV_RD(0, a0, a1, a2, a3); SB();
;                     PV_RD(1, b0_, b1_, b2_, b3_); SB(); PV_MM(0, a0, a1, a2, a3); SB();
;                     PV_RD(2, a0, a1, a2, a3); SB(); PV_MM(1, b0_, b1_, b2_, b3_); SB();
;                     PV_RD(3, b0_, b1_, b2_, b3_); SB(); PV_MM(2, a0, a1, a2, a3); SB();
;                     PV_RD(4, a0, a1, a2, a3); SB(); PV_MM(3, b0_, b1_, b2_, b3_); SB();
.Lattn_region2:
	ds_read_b64_tr_b16 v[216:217], v212 offset:16384
	ds_read_b64_tr_b16 v[218:219], v212 offset:20480
	ds_read_b64_tr_b16 v[220:221], v212 offset:24576
	ds_read_b64_tr_b16 v[222:223], v212 offset:28672
	ds_read_b64_tr_b16 v[236:237], v212 offset:16896
	ds_read_b64_tr_b16 v[238:239], v212 offset:20992
	ds_read_b64_tr_b16 v[240:241], v212 offset:25088
	ds_read_b64_tr_b16 v[242:243], v212 offset:29184
	s_waitcnt lgkmcnt(4)
	v_mfma_f32_32x32x16_bf16 v[114:129], v[132:135], v[216:219], v[114:129]
	v_mfma_f32_32x32x16_bf16 v[114:129], v[136:139], v[220:223], v[114:129]
	v_max3_f32 v226, v140, v141, v142
	v_max3_f32 v226, v226, v143, v144
	v_max3_f32 v226, v226, v145, v146
	v_max3_f32 v226, v226, v147, v148
	v_max3_f32 v226, v226, v149, v150
	v_max3_f32 v226, v226, v151, v152
	v_max3_f32 v226, v226, v153, v154
	ds_read_b64_tr_b16 v[216:217], v212 offset:17408
	ds_read_b64_tr_b16 v[218:219], v212 offset:21504
	ds_read_b64_tr_b16 v[220:221], v212 offset:25600
	ds_read_b64_tr_b16 v[222:223], v212 offset:29696
	s_waitcnt lgkmcnt(4)
	v_mfma_f32_32x32x16_bf16 v[98:113], v[132:135], v[236:239], v[98:113]
	v_max_f32_e32 v226, v226, v155
	v_mov_b32_e32 v227, v226
	s_nop 1
	v_permlane32_swap_b32_e32 v226, v227
	v_max_f32_e32 v226, v226, v227
	v_fma_f32 v226, v226, s82, v231
	v_sub_f32_e32 v227, v226, v213
	v_cmp_ge_f32_e32 vcc, s97, v227
	v_mfma_f32_32x32x16_bf16 v[98:113], v[136:139], v[240:243], v[98:113]
	s_cmp_eq_u64 vcc, exec
	v_max_f32_e32 v226, v213, v226
	s_cselect_b64 vcc, -1, 0
	v_sub_f32_e32 v227, v213, v226
	v_cndmask_b32_e32 v213, v226, v213, vcc
	v_sub_f32_e32 v230, v231, v213
	v_fma_f32 v140, v140, s82, v230
	v_exp_f32_e32 v140, v140
	ds_read_b64_tr_b16 v[236:237], v212 offset:17920
	ds_read_b64_tr_b16 v[238:239], v212 offset:22016
	ds_read_b64_tr_b16 v[240:241], v212 offset:26112
	ds_read_b64_tr_b16 v[242:243], v212 offset:30208
	s_waitcnt lgkmcnt(4)
	v_mfma_f32_32x32x16_bf16 v[82:97], v[132:135], v[216:219], v[82:97]
	v_fma_f32 v141, v141, s82, v230
	v_exp_f32_e32 v141, v141
	v_fma_f32 v142, v142, s82, v230
	v_exp_f32_e32 v142, v142
	v_add_f32_e32 v226, v140, v141
	v_mfma_f32_32x32x16_bf16 v[82:97], v[136:139], v[220:223], v[82:97]
	v_fma_f32 v143, v143, s82, v230
	v_exp_f32_e32 v143, v143
	v_add_f32_e32 v226, v226, v142
	v_fma_f32 v144, v144, s82, v230
	v_exp_f32_e32 v144, v144
	ds_read_b64_tr_b16 v[216:217], v212 offset:18432
	ds_read_b64_tr_b16 v[218:219], v212 offset:22528
	ds_read_b64_tr_b16 v[220:221], v212 offset:26624
	ds_read_b64_tr_b16 v[222:223], v212 offset:30720
	s_waitcnt lgkmcnt(4)
	v_mfma_f32_32x32x16_bf16 v[66:81], v[132:135], v[236:239], v[66:81]
	v_add_f32_e32 v226, v226, v143
	v_fma_f32 v145, v145, s82, v230
	v_exp_f32_e32 v145, v145
	v_add_f32_e32 v226, v226, v144
	v_fma_f32 v146, v146, s82, v230
	v_exp_f32_e32 v146, v146
	v_mfma_f32_32x32x16_bf16 v[66:81], v[136:139], v[240:243], v[66:81]
	v_add_f32_e32 v226, v226, v145
	v_fma_f32 v147, v147, s82, v230
	v_exp_f32_e32 v147, v147
	v_add_f32_e32 v226, v226, v146
	v_fma_f32 v148, v148, s82, v230
	v_exp_f32_e32 v148, v148
	ds_read_b64_tr_b16 v[236:237], v212 offset:18944
	ds_read_b64_tr_b16 v[238:239], v212 offset:23040
	ds_read_b64_tr_b16 v[240:241], v212 offset:27136
	ds_read_b64_tr_b16 v[242:243], v212 offset:31232
	s_waitcnt lgkmcnt(4)
	v_mfma_f32_32x32x16_bf16 v[50:65], v[132:135], v[216:219], v[50:65]
	v_add_f32_e32 v226, v226, v147
	v_fma_f32 v149, v149, s82, v230
	v_exp_f32_e32 v149, v149
	v_add_f32_e32 v226, v226, v148
	v_fma_f32 v150, v150, s82, v230
	v_exp_f32_e32 v150, v150
	v_mfma_f32_32x32x16_bf16 v[50:65], v[136:139], v[220:223], v[50:65]
	v_add_f32_e32 v226, v226, v149
	v_fma_f32 v151, v151, s82, v230
	v_exp_f32_e32 v151, v151
	v_add_f32_e32 v226, v226, v150
	v_fma_f32 v152, v152, s82, v230
	ds_read_b64_tr_b16 v[216:217], v212 offset:19456
	ds_read_b64_tr_b16 v[218:219], v212 offset:23552
	ds_read_b64_tr_b16 v[220:221], v212 offset:27648
	ds_read_b64_tr_b16 v[222:223], v212 offset:31744
	s_waitcnt lgkmcnt(4)
	v_mfma_f32_32x32x16_bf16 v[34:49], v[132:135], v[236:239], v[34:49]
	v_exp_f32_e32 v152, v152
	v_add_f32_e32 v226, v226, v151
	v_fma_f32 v153, v153, s82, v230
	v_exp_f32_e32 v153, v153
	v_mfma_f32_32x32x16_bf16 v[34:49], v[136:139], v[240:243], v[34:49]
	v_add_f32_e32 v226, v226, v152
	v_fma_f32 v154, v154, s82, v230
	v_exp_f32_e32 v154, v154
	v_add_f32_e32 v226, v226, v153
	v_fma_f32 v155, v155, s82, v230
	ds_read_b64_tr_b16 v[236:237], v212 offset:19968
	ds_read_b64_tr_b16 v[238:239], v212 offset:24064
	ds_read_b64_tr_b16 v[240:241], v212 offset:28160
	ds_read_b64_tr_b16 v[242:243], v212 offset:32256
	s_waitcnt lgkmcnt(4)
	v_mfma_f32_32x32x16_bf16 v[18:33], v[132:135], v[216:219], v[18:33]
	v_exp_f32_e32 v155, v155
	v_add_f32_e32 v226, v226, v154
	v_exp_f32_e32 v227, v227
	v_add_f32_e32 v228, v226, v155
	v_mfma_f32_32x32x16_bf16 v[18:33], v[136:139], v[220:223], v[18:33]
	v_cndmask_b32_e64 v227, v227, 1.0, vcc
	v_mov_b32_e32 v229, v228
	v_cvt_pk_bf16_f32 v156, v140, v141
	v_cvt_pk_bf16_f32 v157, v142, v143
	v_cvt_pk_bf16_f32 v158, v144, v145
	v_cvt_pk_bf16_f32 v159, v146, v147
	s_waitcnt lgkmcnt(0)
	v_mfma_f32_32x32x16_bf16 v[2:17], v[132:135], v[236:239], v[2:17]
	v_cvt_pk_bf16_f32 v160, v148, v149
	v_cvt_pk_bf16_f32 v161, v150, v151
	v_cvt_pk_bf16_f32 v162, v152, v153
	v_cvt_pk_bf16_f32 v163, v154, v155
	v_permlane32_swap_b32_e32 v228, v229
	v_permlane32_swap_b32_e32 v156, v158
	v_mfma_f32_32x32x16_bf16 v[2:17], v[136:139], v[240:243], v[2:17]
	v_permlane32_swap_b32_e32 v157, v159
	v_permlane32_swap_b32_e32 v160, v162
	v_permlane32_swap_b32_e32 v161, v163
	v_add_f32_e32 v228, v228, v229
	v_fma_f32 v130, v130, v227, v228
	s_cbranch_vccnz .Lattn_norescale2
; DI int crow(int r, int hi) { return (r & 3) + 8 * (r >> 2) + 4 * hi; }
; DI void phase_attn(int wid0, const Params& p, int L, unsigned char* lds, bool dry) {
;     ...
;                 if (__any(alpha < 1.f)) {
;                     if (hi == 0) al_l[r32] = alpha;
;                     asm volatile("s_waitcnt lgkmcnt(0)" ::: "memory");
;                     float ar[16];
; #pragma unroll
;                     for (int r = 0; r < 16; ++r) ar[r] = al_l[crow(r, hi)];
; #pragma unroll
;                     for (int d = 0; d < 8; ++d)
; #pragma unroll
;                         for (int r = 0; r < 16; ++r) o[d][r] *= ar[r];
;                 }
	s_and_saveexec_b64 s[80:81], s[8:9]
	ds_write_b32 v196, v227 offset:128
	s_or_b64 exec, exec, s[80:81]
	s_waitcnt lgkmcnt(0)
	ds_read_b128 v[152:155], v214 offset:224
	ds_read_b128 v[148:151], v214 offset:192
	ds_read_b128 v[144:147], v214 offset:160
	ds_read_b128 v[140:143], v214 offset:128
	s_waitcnt lgkmcnt(0)
	v_pk_mul_f32 v[126:127], v[126:127], v[152:153]
	v_pk_mul_f32 v[122:123], v[122:123], v[148:149]
	v_pk_mul_f32 v[118:119], v[118:119], v[144:145]
	v_pk_mul_f32 v[128:129], v[128:129], v[154:155]
	v_pk_mul_f32 v[124:125], v[124:125], v[150:151]
	v_pk_mul_f32 v[120:121], v[120:121], v[146:147]
	v_pk_mul_f32 v[116:117], v[116:117], v[142:143]
	v_pk_mul_f32 v[114:115], v[114:115], v[140:141]
	v_pk_mul_f32 v[110:111], v[110:111], v[152:153]
	v_pk_mul_f32 v[106:107], v[106:107], v[148:149]
	v_pk_mul_f32 v[102:103], v[102:103], v[144:145]
	v_pk_mul_f32 v[112:113], v[112:113], v[154:155]
	v_pk_mul_f32 v[108:109], v[108:109], v[150:151]
	v_pk_mul_f32 v[104:105], v[104:105], v[146:147]
	v_pk_mul_f32 v[100:101], v[100:101], v[142:143]
	v_pk_mul_f32 v[98:99], v[98:99], v[140:141]
	v_pk_mul_f32 v[94:95], v[94:95], v[152:153]
	v_pk_mul_f32 v[90:91], v[90:91], v[148:149]
	v_pk_mul_f32 v[86:87], v[86:87], v[144:145]
	v_pk_mul_f32 v[96:97], v[96:97], v[154:155]
	v_pk_mul_f32 v[92:93], v[92:93], v[150:151]
	v_pk_mul_f32 v[88:89], v[88:89], v[146:147]
	v_pk_mul_f32 v[84:85], v[84:85], v[142:143]
	v_pk_mul_f32 v[82:83], v[82:83], v[140:141]
	v_pk_mul_f32 v[78:79], v[78:79], v[152:153]
	v_pk_mul_f32 v[74:75], v[74:75], v[148:149]
	v_pk_mul_f32 v[70:71], v[70:71], v[144:145]
	v_pk_mul_f32 v[80:81], v[80:81], v[154:155]
	v_pk_mul_f32 v[76:77], v[76:77], v[150:151]
	v_pk_mul_f32 v[72:73], v[72:73], v[146:147]
	v_pk_mul_f32 v[68:69], v[68:69], v[142:143]
	v_pk_mul_f32 v[66:67], v[66:67], v[140:141]
	v_pk_mul_f32 v[62:63], v[62:63], v[152:153]
	v_pk_mul_f32 v[58:59], v[58:59], v[148:149]
	v_pk_mul_f32 v[54:55], v[54:55], v[144:145]
	v_pk_mul_f32 v[64:65], v[64:65], v[154:155]
	v_pk_mul_f32 v[60:61], v[60:61], v[150:151]
	v_pk_mul_f32 v[56:57], v[56:57], v[146:147]
	v_pk_mul_f32 v[52:53], v[52:53], v[142:143]
	v_pk_mul_f32 v[50:51], v[50:51], v[140:141]
	v_pk_mul_f32 v[46:47], v[46:47], v[152:153]
	v_pk_mul_f32 v[42:43], v[42:43], v[148:149]
	v_pk_mul_f32 v[38:39], v[38:39], v[144:145]
	v_pk_mul_f32 v[48:49], v[48:49], v[154:155]
	v_pk_mul_f32 v[44:45], v[44:45], v[150:151]
	v_pk_mul_f32 v[40:41], v[40:41], v[146:147]
	v_pk_mul_f32 v[36:37], v[36:37], v[142:143]
	v_pk_mul_f32 v[34:35], v[34:35], v[140:141]
	v_pk_mul_f32 v[30:31], v[30:31], v[152:153]
	v_pk_mul_f32 v[26:27], v[26:27], v[148:149]
	v_pk_mul_f32 v[22:23], v[22:23], v[144:145]
	v_pk_mul_f32 v[32:33], v[32:33], v[154:155]
	v_pk_mul_f32 v[28:29], v[28:29], v[150:151]
	v_pk_mul_f32 v[24:25], v[24:25], v[146:147]
	v_pk_mul_f32 v[20:21], v[20:21], v[142:143]
	v_pk_mul_f32 v[18:19], v[18:19], v[140:141]
	v_pk_mul_f32 v[14:15], v[14:15], v[152:153]
	v_pk_mul_f32 v[10:11], v[10:11], v[148:149]
	v_pk_mul_f32 v[6:7], v[6:7], v[144:145]
	v_pk_mul_f32 v[16:17], v[16:17], v[154:155]
	v_pk_mul_f32 v[12:13], v[12:13], v[150:151]
	v_pk_mul_f32 v[8:9], v[8:9], v[146:147]
	v_pk_mul_f32 v[4:5], v[4:5], v[142:143]
	v_pk_mul_f32 v[2:3], v[2:3], v[140:141]

; #define LAS __attribute__((address_space(3)))
; DI void attn_stage(const bf16_t* kbase, const bf16_t* vbase, unsigned koff, unsigned voff, LAS unsigned char* ldsbuf, int wid) {
; #pragma unroll
;     for (int i = 0; i < 2; ++i) {
;         const char* src = (const char*)kbase + (size_t)(i * 128) * 2;
;         __builtin_amdgcn_global_load_lds((const unsigned*)(src + koff), (LAS unsigned*)(ldsbuf + (wid + 8 * i) * 1024), 16, 0, 0);
;     }
; #pragma unroll
;     for (int i = 0; i < 2; ++i) {
;         const char* src = (const char*)vbase + (size_t)(16 * i * 2048) * 2;
;         __builtin_amdgcn_global_load_lds((const unsigned*)(src + voff), (LAS unsigned*)(ldsbuf + 16384 + (wid + 8 * i) * 1024), 16, 0, 0);
;     }
; }
; DI void phase_attn(int wid0, const Params& p, int L, unsigned char* lds, bool dry) {
;     ...
;             asm volatile("s_waitcnt vmcnt(0) lgkmcnt(0)" ::: "memory"); __builtin_amdgcn_s_barrier(); asm volatile("" ::: "memory");
;             if (t + 1 < ntiles) attn_stage(kh_ + (size_t)(b * 4096 + 32 * t) * 2048, vh_ + (size_t)(b * 4096 + 32 * t) * 2048, koff, voff, ldsl + 65536 + ((t + 1) & 1) * 32768, wid);
;             const int kpos0 = (t == 0) ? 0 : 16 + 32 * (t - 1);
.Lattn_top3:
	s_waitcnt vmcnt(0) lgkmcnt(0)
	s_barrier
	s_cmp_ge_i32 s67, s6
	s_cbranch_scc1 .Lattn_nodma3
	s_add_i32 m0, s4, 0x0
	s_nop 0
	global_load_lds_dwordx4 v131, s[88:89]
	s_add_i32 m0, s4, 0x2000
	s_nop 0
	global_load_lds_dwordx4 v131, s[90:91]
	s_add_i32 m0, s96, 0x0
	v_add_u32_e32 v131, 0x20000, v131
	global_load_lds_dwordx4 v208, s[92:93]
	s_add_i32 m0, s96, 0x2000
	s_nop 0
	global_load_lds_dwordx4 v208, s[94:95]
	v_add_u32_e32 v208, 0x20000, v208

; DI void phase_attn(int wid0, const Params& p, int L, unsigned char* lds, bool dry) {
;     ...
;                 float pmax = p0[0];
; #pragma unroll
;                 for (int r = 1; r < 16; ++r) pmax = fmaxf(pmax, p0[r]);
;                 { auto rr = __builtin_amdgcn_permlane32_swap(__float_as_uint(pmax), __float_as_uint(pmax), false, false); pmax = fmaxf(__uint_as_float(rr[0]), __uint_as_float(rr[1])); }
;                 float mn, alpha;
;                 if (__all(pmax - m_reg <= ATT_THR2)) { mn = m_reg; alpha = 1.f; }
;                 else { mn = fmaxf(m_reg, pmax); alpha = __builtin_amdgcn_exp2f(m_reg - mn); m_reg = mn; }
;                 float ps = 0.f;
; #pragma unroll
;                 for (int r = 0; r < 16; ++r) { p0[r] = __builtin_amdgcn_exp2f(p0[r] - mn); ps += p0[r]; }
;                 { auto rr = __builtin_amdgcn_permlane32_swap(__float_as_uint(ps), __float_as_uint(ps), false, false); ps = __uint_as_float(rr[0]) + __uint_as_float(rr[1]); }
;                 l_reg = l_reg * alpha + ps;
;                 __builtin_amdgcn_sched_barrier(0);
;                 bf16x8 pa0, pa1;
;     ...
;                 PK4(p0, 0, pa0); PK4(p0, 8, pa1);
;     ...
;                 __builtin_amdgcn_sched_barrier(0);
;                 if (__any(alpha < 1.f)) {
;                     if (hi == 0) al_l[r32] = alpha;
;                     asm volatile("s_waitcnt lgkmcnt(0)" ::: "memory");
;                     float ar[16];
; #pragma unroll
;                     for (int r = 0; r < 16; ++r) ar[r] = al_l[crow(r, hi)];
; #pragma unroll
;                     for (int d = 0; d < 8; ++d)
; #pragma unroll
;                         for (int r = 0; r < 16; ++r) o[d][r] *= ar[r];
;                 }
;                 __builtin_amdgcn_sched_barrier(0);
;                 LAS unsigned char* vbp = ldsl + 65536 + (t & 1) * 32768 + 16384 + v_rd_base(lane);
;                 __builtin_amdgcn_s_setprio(1);
;     ...
;                 {
;                     s16x4 a0, a1, a2, a3, b0_, b1_, b2_, b3_;
;                     PV_RD(0, a0, a1, a2, a3); SB();
;                     PV_RD(1, b0_, b1_, b2_, b3_); SB(); PV_MM(0, a0, a1, a2, a3); SB();
;                     PV_RD(2, a0, a1, a2, a3); SB(); PV_MM(1, b0_, b1_, b2_, b3_); SB();
;                     PV_RD(3, b0_, b1_, b2_, b3_); SB(); PV_MM(2, a0, a1, a2, a3); SB();
;                     PV_RD(4, a0, a1, a2, a3); SB(); PV_MM(3, b0_, b1_, b2_, b3_); SB();
.Lattn_region3:
	ds_read_b64_tr_b16 v[216:217], v212 offset:32768
	ds_read_b64_tr_b16 v[218:219], v212 offset:36864
	ds_read_b64_tr_b16 v[220:221], v212 offset:40960
	ds_read_b64_tr_b16 v[222:223], v212 offset:45056
	ds_read_b64_tr_b16 v[236:237], v212 offset:33280
	ds_read_b64_tr_b16 v[238:239], v212 offset:37376
	ds_read_b64_tr_b16 v[240:241], v212 offset:41472
	ds_read_b64_tr_b16 v[242:243], v212 offset:45568
	s_waitcnt lgkmcnt(4)
	v_mfma_f32_32x32x16_bf16 v[114:129], v[156:159], v[216:219], v[114:129]
	v_mfma_f32_32x32x16_bf16 v[114:129], v[160:163], v[220:223], v[114:129]
	v_max3_f32 v226, v140, v141, v142
	v_max3_f32 v226, v226, v143, v144
	v_max3_f32 v226, v226, v145, v146
	v_max3_f32 v226, v226, v147, v148
	v_max3_f32 v226, v226, v149, v150
	v_max3_f32 v226, v226, v151, v152
	v_max3_f32 v226, v226, v153, v154
	ds_read_b64_tr_b16 v[216:217], v212 offset:33792
	ds_read_b64_tr_b16 v[218:219], v212 offset:37888
	ds_read_b64_tr_b16 v[220:221], v212 offset:41984
	ds_read_b64_tr_b16 v[222:223], v212 offset:46080
	s_waitcnt lgkmcnt(4)
	v_mfma_f32_32x32x16_bf16 v[98:113], v[156:159], v[236:239], v[98:113]
	v_max_f32_e32 v226, v226, v155
	v_mov_b32_e32 v227, v226
	s_nop 1
	v_permlane32_swap_b32_e32 v226, v227
	v_max_f32_e32 v226, v226, v227
	v_fma_f32 v226, v226, s82, v231
	v_sub_f32_e32 v227, v226, v213
	v_cmp_ge_f32_e32 vcc, s97, v227
	v_mfma_f32_32x32x16_bf16 v[98:113], v[160:163], v[240:243], v[98:113]
	s_cmp_eq_u64 vcc, exec
	v_max_f32_e32 v226, v213, v226
	s_cselect_b64 vcc, -1, 0
	v_sub_f32_e32 v227, v213, v226
	v_cndmask_b32_e32 v213, v226, v213, vcc
	v_sub_f32_e32 v230, v231, v213
	v_fma_f32 v140, v140, s82, v230
	v_exp_f32_e32 v140, v140
	ds_read_b64_tr_b16 v[236:237], v212 offset:34304
	ds_read_b64_tr_b16 v[238:239], v212 offset:38400
	ds_read_b64_tr_b16 v[240:241], v212 offset:42496
	ds_read_b64_tr_b16 v[242:243], v212 offset:46592
	s_waitcnt lgkmcnt(4)
	v_mfma_f32_32x32x16_bf16 v[82:97], v[156:159], v[216:219], v[82:97]
	v_fma_f32 v141, v141, s82, v230
	v_exp_f32_e32 v141, v141
	v_fma_f32 v142, v142, s82, v230
	v_exp_f32_e32 v142, v142
	v_add_f32_e32 v226, v140, v141
	v_mfma_f32_32x32x16_bf16 v[82:97], v[160:163], v[220:223], v[82:97]
	v_fma_f32 v143, v143, s82, v230
	v_exp_f32_e32 v143, v143
	v_add_f32_e32 v226, v226, v142
	v_fma_f32 v144, v144, s82, v230
	v_exp_f32_e32 v144, v144
	ds_read_b64_tr_b16 v[216:217], v212 offset:34816
	ds_read_b64_tr_b16 v[218:219], v212 offset:38912
	ds_read_b64_tr_b16 v[220:221], v212 offset:43008
	ds_read_b64_tr_b16 v[222:223], v212 offset:47104
	s_waitcnt lgkmcnt(4)
	v_mfma_f32_32x32x16_bf16 v[66:81], v[156:159], v[236:239], v[66:81]
	v_add_f32_e32 v226, v226, v143
	v_fma_f32 v145, v145, s82, v230
	v_exp_f32_e32 v145, v145
	v_add_f32_e32 v226, v226, v144
	v_fma_f32 v146, v146, s82, v230
	v_exp_f32_e32 v146, v146
	v_mfma_f32_32x32x16_bf16 v[66:81], v[160:163], v[240:243], v[66:81]
	v_add_f32_e32 v226, v226, v145
	v_fma_f32 v147, v147, s82, v230
	v_exp_f32_e32 v147, v147
	v_add_f32_e32 v226, v226, v146
	v_fma_f32 v148, v148, s82, v230
	v_exp_f32_e32 v148, v148
	ds_read_b64_tr_b16 v[236:237], v212 offset:35328
	ds_read_b64_tr_b16 v[238:239], v212 offset:39424
	ds_read_b64_tr_b16 v[240:241], v212 offset:43520
	ds_read_b64_tr_b16 v[242:243], v212 offset:47616
	s_waitcnt lgkmcnt(4)
	v_mfma_f32_32x32x16_bf16 v[50:65], v[156:159], v[216:219], v[50:65]
	v_add_f32_e32 v226, v226, v147
	v_fma_f32 v149, v149, s82, v230
	v_exp_f32_e32 v149, v149
	v_add_f32_e32 v226, v226, v148
	v_fma_f32 v150, v150, s82, v230
	v_exp_f32_e32 v150, v150
	v_mfma_f32_32x32x16_bf16 v[50:65], v[160:163], v[220:223], v[50:65]
	v_add_f32_e32 v226, v226, v149
	v_fma_f32 v151, v151, s82, v230
	v_exp_f32_e32 v151, v151
	v_add_f32_e32 v226, v226, v150
	v_fma_f32 v152, v152, s82, v230
	ds_read_b64_tr_b16 v[216:217], v212 offset:35840
	ds_read_b64_tr_b16 v[218:219], v212 offset:39936
	ds_read_b64_tr_b16 v[220:221], v212 offset:44032
	ds_read_b64_tr_b16 v[222:223], v212 offset:48128
	s_waitcnt lgkmcnt(4)
	v_mfma_f32_32x32x16_bf16 v[34:49], v[156:159], v[236:239], v[34:49]
	v_exp_f32_e32 v152, v152
	v_add_f32_e32 v226, v226, v151
	v_fma_f32 v153, v153, s82, v230
	v_exp_f32_e32 v153, v153
	v_mfma_f32_32x32x16_bf16 v[34:49], v[160:163], v[240:243], v[34:49]
	v_add_f32_e32 v226, v226, v152
	v_fma_f32 v154, v154, s82, v230
	v_exp_f32_e32 v154, v154
	v_add_f32_e32 v226, v226, v153
	v_fma_f32 v155, v155, s82, v230
	ds_read_b64_tr_b16 v[236:237], v212 offset:36352
	ds_read_b64_tr_b16 v[238:239], v212 offset:40448
	ds_read_b64_tr_b16 v[240:241], v212 offset:44544
	ds_read_b64_tr_b16 v[242:243], v212 offset:48640
	s_waitcnt lgkmcnt(4)
	v_mfma_f32_32x32x16_bf16 v[18:33], v[156:159], v[216:219], v[18:33]
	v_exp_f32_e32 v155, v155
	v_add_f32_e32 v226, v226, v154
	v_exp_f32_e32 v227, v227
	v_add_f32_e32 v228, v226, v155
	v_mfma_f32_32x32x16_bf16 v[18:33], v[160:163], v[220:223], v[18:33]
	v_cndmask_b32_e64 v227, v227, 1.0, vcc
	v_mov_b32_e32 v229, v228
	v_cvt_pk_bf16_f32 v132, v140, v141
	v_cvt_pk_bf16_f32 v133, v142, v143
	v_cvt_pk_bf16_f32 v134, v144, v145
	v_cvt_pk_bf16_f32 v135, v146, v147
	s_waitcnt lgkmcnt(0)
	v_mfma_f32_32x32x16_bf16 v[2:17], v[156:159], v[236:239], v[2:17]
	v_cvt_pk_bf16_f32 v136, v148, v149
	v_cvt_pk_bf16_f32 v137, v150, v151
	v_cvt_pk_bf16_f32 v138, v152, v153
	v_cvt_pk_bf16_f32 v139, v154, v155
	v_permlane32_swap_b32_e32 v228, v229
	v_permlane32_swap_b32_e32 v132, v134
	v_mfma_f32_32x32x16_bf16 v[2:17], v[160:163], v[240:243], v[2:17]
	v_permlane32_swap_b32_e32 v133, v135
	v_permlane32_swap_b32_e32 v136, v138
	v_permlane32_swap_b32_e32 v137, v139
	v_add_f32_e32 v228, v228, v229
	v_fma_f32 v130, v130, v227, v228
	s_cbranch_vccnz .Lattn_norescale3
; DI int crow(int r, int hi) { return (r & 3) + 8 * (r >> 2) + 4 * hi; }
; DI void phase_attn(int wid0, const Params& p, int L, unsigned char* lds, bool dry) {
;     ...
;         for (int t = 0; t < ntiles; ++t) {
;             asm volatile("s_waitcnt vmcnt(0) lgkmcnt(0)" ::: "memory"); __builtin_amdgcn_s_barrier(); asm volatile("" ::: "memory");
;             if (t + 1 < ntiles) attn_stage(kh_ + (size_t)(b * 4096 + 32 * t) * 2048, vh_ + (size_t)(b * 4096 + 32 * t) * 2048, koff, voff, ldsl + 65536 + ((t + 1) & 1) * 32768, wid);
;             const int kpos0 = (t == 0) ? 0 : 16 + 32 * (t - 1);
;     ...
;                 if (__any(alpha < 1.f)) {
;                     if (hi == 0) al_l[r32] = alpha;
;                     asm volatile("s_waitcnt lgkmcnt(0)" ::: "memory");
;                     float ar[16];
; #pragma unroll
;                     for (int r = 0; r < 16; ++r) ar[r] = al_l[crow(r, hi)];
; #pragma unroll
;                     for (int d = 0; d < 8; ++d)
; #pragma unroll
;                         for (int r = 0; r < 16; ++r) o[d][r] *= ar[r];
;                 }
	s_and_saveexec_b64 s[80:81], s[8:9]
	ds_write_b32 v196, v227 offset:128
	s_or_b64 exec, exec, s[80:81]
	s_waitcnt lgkmcnt(0)
	ds_read_b128 v[152:155], v214 offset:224
	ds_read_b128 v[148:151], v214 offset:192
	ds_read_b128 v[144:147], v214 offset:160
	ds_read_b128 v[140:143], v214 offset:128
	s_waitcnt lgkmcnt(0)
	v_pk_mul_f32 v[126:127], v[126:127], v[152:153]
	v_pk_mul_f32 v[122:123], v[122:123], v[148:149]
	v_pk_mul_f32 v[118:119], v[118:119], v[144:145]
	v_pk_mul_f32 v[128:129], v[128:129], v[154:155]
	v_pk_mul_f32 v[124:125], v[124:125], v[150:151]
	v_pk_mul_f32 v[120:121], v[120:121], v[146:147]
	v_pk_mul_f32 v[116:117], v[116:117], v[142:143]
	v_pk_mul_f32 v[114:115], v[114:115], v[140:141]
	v_pk_mul_f32 v[110:111], v[110:111], v[152:153]
	v_pk_mul_f32 v[106:107], v[106:107], v[148:149]
	v_pk_mul_f32 v[102:103], v[102:103], v[144:145]
	v_pk_mul_f32 v[112:113], v[112:113], v[154:155]
	v_pk_mul_f32 v[108:109], v[108:109], v[150:151]
	v_pk_mul_f32 v[104:105], v[104:105], v[146:147]
	v_pk_mul_f32 v[100:101], v[100:101], v[142:143]
	v_pk_mul_f32 v[98:99], v[98:99], v[140:141]
	v_pk_mul_f32 v[94:95], v[94:95], v[152:153]
	v_pk_mul_f32 v[90:91], v[90:91], v[148:149]
	v_pk_mul_f32 v[86:87], v[86:87], v[144:145]
	v_pk_mul_f32 v[96:97], v[96:97], v[154:155]
	v_pk_mul_f32 v[92:93], v[92:93], v[150:151]
	v_pk_mul_f32 v[88:89], v[88:89], v[146:147]
	v_pk_mul_f32 v[84:85], v[84:85], v[142:143]
	v_pk_mul_f32 v[82:83], v[82:83], v[140:141]
	v_pk_mul_f32 v[78:79], v[78:79], v[152:153]
	v_pk_mul_f32 v[74:75], v[74:75], v[148:149]
	v_pk_mul_f32 v[70:71], v[70:71], v[144:145]
	v_pk_mul_f32 v[80:81], v[80:81], v[154:155]
	v_pk_mul_f32 v[76:77], v[76:77], v[150:151]
	v_pk_mul_f32 v[72:73], v[72:73], v[146:147]
	v_pk_mul_f32 v[68:69], v[68:69], v[142:143]
	v_pk_mul_f32 v[66:67], v[66:67], v[140:141]
	v_pk_mul_f32 v[62:63], v[62:63], v[152:153]
	v_pk_mul_f32 v[58:59], v[58:59], v[148:149]
	v_pk_mul_f32 v[54:55], v[54:55], v[144:145]
	v_pk_mul_f32 v[64:65], v[64:65], v[154:155]
	v_pk_mul_f32 v[60:61], v[60:61], v[150:151]
	v_pk_mul_f32 v[56:57], v[56:57], v[146:147]
	v_pk_mul_f32 v[52:53], v[52:53], v[142:143]
	v_pk_mul_f32 v[50:51], v[50:51], v[140:141]
	v_pk_mul_f32 v[46:47], v[46:47], v[152:153]
	v_pk_mul_f32 v[42:43], v[42:43], v[148:149]
	v_pk_mul_f32 v[38:39], v[38:39], v[144:145]
	v_pk_mul_f32 v[48:49], v[48:49], v[154:155]
	v_pk_mul_f32 v[44:45], v[44:45], v[150:151]
	v_pk_mul_f32 v[40:41], v[40:41], v[146:147]
	v_pk_mul_f32 v[36:37], v[36:37], v[142:143]
	v_pk_mul_f32 v[34:35], v[34:35], v[140:141]
	v_pk_mul_f32 v[30:31], v[30:31], v[152:153]
	v_pk_mul_f32 v[26:27], v[26:27], v[148:149]
	v_pk_mul_f32 v[22:23], v[22:23], v[144:145]
	v_pk_mul_f32 v[32:33], v[32:33], v[154:155]
	v_pk_mul_f32 v[28:29], v[28:29], v[150:151]
	v_pk_mul_f32 v[24:25], v[24:25], v[146:147]
	v_pk_mul_f32 v[20:21], v[20:21], v[142:143]
	v_pk_mul_f32 v[18:19], v[18:19], v[140:141]
	v_pk_mul_f32 v[14:15], v[14:15], v[152:153]
	v_pk_mul_f32 v[10:11], v[10:11], v[148:149]
	v_pk_mul_f32 v[6:7], v[6:7], v[144:145]
	v_pk_mul_f32 v[16:17], v[16:17], v[154:155]
	v_pk_mul_f32 v[12:13], v[12:13], v[150:151]
	v_pk_mul_f32 v[8:9], v[8:9], v[146:147]
	v_pk_mul_f32 v[4:5], v[4:5], v[142:143]
	v_pk_mul_f32 v[2:3], v[2:3], v[140:141]
.Lattn_norescale3:
.Lattn_latch3:
	s_sub_i32 s39, s39, 32
	s_add_i32 s7, s7, 32
	s_cmp_eq_u32 s6, s67
	s_cbranch_scc1 .Lattn_exit3
	s_add_i32 s67, s67, 1
	s_branch .LBB0_99

; #define LAS __attribute__((address_space(3)))
; DI int v_rd_base(int lane) { return ((lane & 3) << 3) | (((lane >> 2) & 3) << 6) | (((lane >> 4) & 1) << 5) | (((lane >> 5) & 1) << 8); }
; #define PV_RD(D0, L0, H0, L1, H1) L0 = TRB(v_rd_off(D0, 0, 0)); H0 = TRB(v_rd_off(D0, 0, 1)); L1 = TRB(v_rd_off(D0, 1, 0)); H1 = TRB(v_rd_off(D0, 1, 1))
; #define PV_MM(D0, L0, H0, L1, H1) o[D0] = MFMA32(pa0, PK8(L0, H0), o[D0]); o[D0] = MFMA32(pa1, PK8(L1, H1), o[D0])
; #define SB() __builtin_amdgcn_sched_barrier(0)
; DI void phase_attn(int wid0, const Params& p, int L, unsigned char* lds, bool dry) {
;     ...
;                 LAS unsigned char* vbp = ldsl + 65536 + (t & 1) * 32768 + 16384 + v_rd_base(lane);
;                 __builtin_amdgcn_s_setprio(1);
;     ...
;                 {
;                     s16x4 a0, a1, a2, a3, b0_, b1_, b2_, b3_;
;                     PV_RD(0, a0, a1, a2, a3); SB();
;                     PV_RD(1, b0_, b1_, b2_, b3_); SB(); PV_MM(0, a0, a1, a2, a3); SB();
;                     PV_RD(2, a0, a1, a2, a3); SB(); PV_MM(1, b0_, b1_, b2_, b3_); SB();
;                     PV_RD(3, b0_, b1_, b2_, b3_); SB(); PV_MM(2, a0, a1, a2, a3); SB();
;                     PV_RD(4, a0, a1, a2, a3); SB(); PV_MM(3, b0_, b1_, b2_, b3_); SB();
;                     PV_RD(5, b0_, b1_, b2_, b3_); SB(); PV_MM(4, a0, a1, a2, a3); SB();
;                     PV_RD(6, a0, a1, a2, a3); SB(); PV_MM(5, b0_, b1_, b2_, b3_); SB();
;                     PV_RD(7, b0_, b1_, b2_, b3_); SB(); PV_MM(6, a0, a1, a2, a3); SB();
;                     PV_MM(7, b0_, b1_, b2_, b3_); SB();
;                 }
;     ...
;                 __builtin_amdgcn_s_setprio(0);
.Lattn_pvplain3:
	s_setprio 1
	ds_read_b64_tr_b16 v[140:141], v212 offset:49152
	ds_read_b64_tr_b16 v[142:143], v212 offset:53248
	ds_read_b64_tr_b16 v[144:145], v212 offset:57344
	ds_read_b64_tr_b16 v[146:147], v212 offset:61440
	ds_read_b64_tr_b16 v[148:149], v212 offset:49664
	ds_read_b64_tr_b16 v[150:151], v212 offset:53760
	ds_read_b64_tr_b16 v[152:153], v212 offset:57856
	ds_read_b64_tr_b16 v[154:155], v212 offset:61952
	s_waitcnt lgkmcnt(6)
	v_mfma_f32_32x32x16_bf16 v[114:129], v[132:135], v[140:143], v[114:129]
	s_waitcnt lgkmcnt(4)
	v_mfma_f32_32x32x16_bf16 v[114:129], v[136:139], v[144:147], v[114:129]
	ds_read_b64_tr_b16 v[140:141], v212 offset:50176
	ds_read_b64_tr_b16 v[142:143], v212 offset:54272
	ds_read_b64_tr_b16 v[144:145], v212 offset:58368
	ds_read_b64_tr_b16 v[146:147], v212 offset:62464
	s_waitcnt lgkmcnt(6)
	v_mfma_f32_32x32x16_bf16 v[98:113], v[132:135], v[148:151], v[98:113]
	s_waitcnt lgkmcnt(4)
	v_mfma_f32_32x32x16_bf16 v[98:113], v[136:139], v[152:155], v[98:113]
	ds_read_b64_tr_b16 v[148:149], v212 offset:50688
	ds_read_b64_tr_b16 v[150:151], v212 offset:54784
	ds_read_b64_tr_b16 v[152:153], v212 offset:58880
	ds_read_b64_tr_b16 v[154:155], v212 offset:62976
	s_waitcnt lgkmcnt(6)
	v_mfma_f32_32x32x16_bf16 v[82:97], v[132:135], v[140:143], v[82:97]
	s_waitcnt lgkmcnt(4)
	v_mfma_f32_32x32x16_bf16 v[82:97], v[136:139], v[144:147], v[82:97]
	ds_read_b64_tr_b16 v[140:141], v212 offset:51200
	ds_read_b64_tr_b16 v[142:143], v212 offset:55296
	ds_read_b64_tr_b16 v[144:145], v212 offset:59392
	ds_read_b64_tr_b16 v[146:147], v212 offset:63488
	s_waitcnt lgkmcnt(6)
	v_mfma_f32_32x32x16_bf16 v[66:81], v[132:135], v[148:151], v[66:81]
	s_waitcnt lgkmcnt(4)
	v_mfma_f32_32x32x16_bf16 v[66:81], v[136:139], v[152:155], v[66:81]
	ds_read_b64_tr_b16 v[148:149], v212 offset:51712
	ds_read_b64_tr_b16 v[150:151], v212 offset:55808
	ds_read_b64_tr_b16 v[152:153], v212 offset:59904
	ds_read_b64_tr_b16 v[154:155], v212 offset:64000
	s_waitcnt lgkmcnt(6)
	v_mfma_f32_32x32x16_bf16 v[50:65], v[132:135], v[140:143], v[50:65]
	s_waitcnt lgkmcnt(4)
	v_mfma_f32_32x32x16_bf16 v[50:65], v[136:139], v[144:147], v[50:65]
	ds_read_b64_tr_b16 v[140:141], v212 offset:52224
	ds_read_b64_tr_b16 v[142:143], v212 offset:56320
	ds_read_b64_tr_b16 v[144:145], v212 offset:60416
	ds_read_b64_tr_b16 v[146:147], v212 offset:64512
	s_waitcnt lgkmcnt(6)
	v_mfma_f32_32x32x16_bf16 v[34:49], v[132:135], v[148:151], v[34:49]
	s_waitcnt lgkmcnt(4)
	v_mfma_f32_32x32x16_bf16 v[34:49], v[136:139], v[152:155], v[34:49]
	ds_read_b64_tr_b16 v[148:149], v212 offset:52736
	ds_read_b64_tr_b16 v[150:151], v212 offset:56832
	ds_read_b64_tr_b16 v[152:153], v212 offset:60928
	ds_read_b64_tr_b16 v[154:155], v212 offset:65024
	s_waitcnt lgkmcnt(6)
	v_mfma_f32_32x32x16_bf16 v[18:33], v[132:135], v[140:143], v[18:33]
	s_waitcnt lgkmcnt(4)
	v_mfma_f32_32x32x16_bf16 v[18:33], v[136:139], v[144:147], v[18:33]
	s_waitcnt lgkmcnt(2)
	v_mfma_f32_32x32x16_bf16 v[2:17], v[132:135], v[148:151], v[2:17]
	s_waitcnt lgkmcnt(0)
	v_mfma_f32_32x32x16_bf16 v[2:17], v[136:139], v[152:155], v[2:17]
	s_setprio 0
	s_andn2_b32 s100, s100, 0x100
	s_bitcmp1_b32 s100, 9
	s_cbranch_scc1 .LBB0_113
	s_branch .Lattn_latch0

; #define LAS __attribute__((address_space(3)))
; DI int v_rd_base(int lane) { return ((lane & 3) << 3) | (((lane >> 2) & 3) << 6) | (((lane >> 4) & 1) << 5) | (((lane >> 5) & 1) << 8); }
; #define PV_RD(D0, L0, H0, L1, H1) L0 = TRB(v_rd_off(D0, 0, 0)); H0 = TRB(v_rd_off(D0, 0, 1)); L1 = TRB(v_rd_off(D0, 1, 0)); H1 = TRB(v_rd_off(D0, 1, 1))
; #define PV_MM(D0, L0, H0, L1, H1) o[D0] = MFMA32(pa0, PK8(L0, H0), o[D0]); o[D0] = MFMA32(pa1, PK8(L1, H1), o[D0])
; #define SB() __builtin_amdgcn_sched_barrier(0)
; DI void phase_attn(int wid0, const Params& p, int L, unsigned char* lds, bool dry) {
;     ...
;                 LAS unsigned char* vbp = ldsl + 65536 + (t & 1) * 32768 + 16384 + v_rd_base(lane);
;                 __builtin_amdgcn_s_setprio(1);
;     ...
;                 {
;                     s16x4 a0, a1, a2, a3, b0_, b1_, b2_, b3_;
;                     PV_RD(0, a0, a1, a2, a3); SB();
;                     PV_RD(1, b0_, b1_, b2_, b3_); SB(); PV_MM(0, a0, a1, a2, a3); SB();
;                     PV_RD(2, a0, a1, a2, a3); SB(); PV_MM(1, b0_, b1_, b2_, b3_); SB();
;                     PV_RD(3, b0_, b1_, b2_, b3_); SB(); PV_MM(2, a0, a1, a2, a3); SB();
;                     PV_RD(4, a0, a1, a2, a3); SB(); PV_MM(3, b0_, b1_, b2_, b3_); SB();
;                     PV_RD(5, b0_, b1_, b2_, b3_); SB(); PV_MM(4, a0, a1, a2, a3); SB();
;                     PV_RD(6, a0, a1, a2, a3); SB(); PV_MM(5, b0_, b1_, b2_, b3_); SB();
;                     PV_RD(7, b0_, b1_, b2_, b3_); SB(); PV_MM(6, a0, a1, a2, a3); SB();
;                     PV_MM(7, b0_, b1_, b2_, b3_); SB();
;                 }
;     ...
;                 __builtin_amdgcn_s_setprio(0);
.Lattn_pvplain0:
	s_setprio 1
	ds_read_b64_tr_b16 v[140:141], v212 offset:0
	ds_read_b64_tr_b16 v[142:143], v212 offset:4096
	ds_read_b64_tr_b16 v[144:145], v212 offset:8192
	ds_read_b64_tr_b16 v[146:147], v212 offset:12288
	ds_read_b64_tr_b16 v[148:149], v212 offset:512
	ds_read_b64_tr_b16 v[150:151], v212 offset:4608
	ds_read_b64_tr_b16 v[152:153], v212 offset:8704
	ds_read_b64_tr_b16 v[154:155], v212 offset:12800
	s_waitcnt lgkmcnt(6)
	v_mfma_f32_32x32x16_bf16 v[114:129], v[156:159], v[140:143], v[114:129]
	s_waitcnt lgkmcnt(4)
	v_mfma_f32_32x32x16_bf16 v[114:129], v[160:163], v[144:147], v[114:129]
	ds_read_b64_tr_b16 v[140:141], v212 offset:1024
	ds_read_b64_tr_b16 v[142:143], v212 offset:5120
	ds_read_b64_tr_b16 v[144:145], v212 offset:9216
	ds_read_b64_tr_b16 v[146:147], v212 offset:13312
	s_waitcnt lgkmcnt(6)
	v_mfma_f32_32x32x16_bf16 v[98:113], v[156:159], v[148:151], v[98:113]
	s_waitcnt lgkmcnt(4)
	v_mfma_f32_32x32x16_bf16 v[98:113], v[160:163], v[152:155], v[98:113]
	ds_read_b64_tr_b16 v[148:149], v212 offset:1536
	ds_read_b64_tr_b16 v[150:151], v212 offset:5632
	ds_read_b64_tr_b16 v[152:153], v212 offset:9728
	ds_read_b64_tr_b16 v[154:155], v212 offset:13824
	s_waitcnt lgkmcnt(6)
	v_mfma_f32_32x32x16_bf16 v[82:97], v[156:159], v[140:143], v[82:97]
	s_waitcnt lgkmcnt(4)
	v_mfma_f32_32x32x16_bf16 v[82:97], v[160:163], v[144:147], v[82:97]
	ds_read_b64_tr_b16 v[140:141], v212 offset:2048
	ds_read_b64_tr_b16 v[142:143], v212 offset:6144
	ds_read_b64_tr_b16 v[144:145], v212 offset:10240
	ds_read_b64_tr_b16 v[146:147], v212 offset:14336
	s_waitcnt lgkmcnt(6)
	v_mfma_f32_32x32x16_bf16 v[66:81], v[156:159], v[148:151], v[66:81]
	s_waitcnt lgkmcnt(4)
	v_mfma_f32_32x32x16_bf16 v[66:81], v[160:163], v[152:155], v[66:81]
	ds_read_b64_tr_b16 v[148:149], v212 offset:2560
	ds_read_b64_tr_b16 v[150:151], v212 offset:6656
	ds_read_b64_tr_b16 v[152:153], v212 offset:10752
	ds_read_b64_tr_b16 v[154:155], v212 offset:14848
	s_waitcnt lgkmcnt(6)
	v_mfma_f32_32x32x16_bf16 v[50:65], v[156:159], v[140:143], v[50:65]
	s_waitcnt lgkmcnt(4)
	v_mfma_f32_32x32x16_bf16 v[50:65], v[160:163], v[144:147], v[50:65]
	ds_read_b64_tr_b16 v[140:141], v212 offset:3072
	ds_read_b64_tr_b16 v[142:143], v212 offset:7168
	ds_read_b64_tr_b16 v[144:145], v212 offset:11264
	ds_read_b64_tr_b16 v[146:147], v212 offset:15360
	s_waitcnt lgkmcnt(6)
	v_mfma_f32_32x32x16_bf16 v[34:49], v[156:159], v[148:151], v[34:49]
	s_waitcnt lgkmcnt(4)
	v_mfma_f32_32x32x16_bf16 v[34:49], v[160:163], v[152:155], v[34:49]
	ds_read_b64_tr_b16 v[148:149], v212 offset:3584
	ds_read_b64_tr_b16 v[150:151], v212 offset:7680
	ds_read_b64_tr_b16 v[152:153], v212 offset:11776
	ds_read_b64_tr_b16 v[154:155], v212 offset:15872
	s_waitcnt lgkmcnt(6)
	v_mfma_f32_32x32x16_bf16 v[18:33], v[156:159], v[140:143], v[18:33]
	s_waitcnt lgkmcnt(4)
	v_mfma_f32_32x32x16_bf16 v[18:33], v[160:163], v[144:147], v[18:33]
	s_waitcnt lgkmcnt(2)
	v_mfma_f32_32x32x16_bf16 v[2:17], v[156:159], v[148:151], v[2:17]
	s_waitcnt lgkmcnt(0)
	v_mfma_f32_32x32x16_bf16 v[2:17], v[160:163], v[152:155], v[2:17]
	s_setprio 0
	s_andn2_b32 s100, s100, 0x100
	s_bitcmp1_b32 s100, 9
	s_cbranch_scc1 .LBB0_113
	s_branch .Lattn_latch1

; #define LAS __attribute__((address_space(3)))
; DI int v_rd_base(int lane) { return ((lane & 3) << 3) | (((lane >> 2) & 3) << 6) | (((lane >> 4) & 1) << 5) | (((lane >> 5) & 1) << 8); }
; #define PV_RD(D0, L0, H0, L1, H1) L0 = TRB(v_rd_off(D0, 0, 0)); H0 = TRB(v_rd_off(D0, 0, 1)); L1 = TRB(v_rd_off(D0, 1, 0)); H1 = TRB(v_rd_off(D0, 1, 1))
; #define PV_MM(D0, L0, H0, L1, H1) o[D0] = MFMA32(pa0, PK8(L0, H0), o[D0]); o[D0] = MFMA32(pa1, PK8(L1, H1), o[D0])
; #define SB() __builtin_amdgcn_sched_barrier(0)
; DI void phase_attn(int wid0, const Params& p, int L, unsigned char* lds, bool dry) {
;     ...
;                 LAS unsigned char* vbp = ldsl + 65536 + (t & 1) * 32768 + 16384 + v_rd_base(lane);
;                 __builtin_amdgcn_s_setprio(1);
;     ...
;                 {
;                     s16x4 a0, a1, a2, a3, b0_, b1_, b2_, b3_;
;                     PV_RD(0, a0, a1, a2, a3); SB();
;                     PV_RD(1, b0_, b1_, b2_, b3_); SB(); PV_MM(0, a0, a1, a2, a3); SB();
;                     PV_RD(2, a0, a1, a2, a3); SB(); PV_MM(1, b0_, b1_, b2_, b3_); SB();
;                     PV_RD(3, b0_, b1_, b2_, b3_); SB(); PV_MM(2, a0, a1, a2, a3); SB();
;                     PV_RD(4, a0, a1, a2, a3); SB(); PV_MM(3, b0_, b1_, b2_, b3_); SB();
;                     PV_RD(5, b0_, b1_, b2_, b3_); SB(); PV_MM(4, a0, a1, a2, a3); SB();
;                     PV_RD(6, a0, a1, a2, a3); SB(); PV_MM(5, b0_, b1_, b2_, b3_); SB();
;                     PV_RD(7, b0_, b1_, b2_, b3_); SB(); PV_MM(6, a0, a1, a2, a3); SB();
;                     PV_MM(7, b0_, b1_, b2_, b3_); SB();
;                 }
;     ...
;                 __builtin_amdgcn_s_setprio(0);
.Lattn_pvplain1:
	s_setprio 1
	ds_read_b64_tr_b16 v[140:141], v212 offset:16384
	ds_read_b64_tr_b16 v[142:143], v212 offset:20480
	ds_read_b64_tr_b16 v[144:145], v212 offset:24576
	ds_read_b64_tr_b16 v[146:147], v212 offset:28672
	ds_read_b64_tr_b16 v[148:149], v212 offset:16896
	ds_read_b64_tr_b16 v[150:151], v212 offset:20992
	ds_read_b64_tr_b16 v[152:153], v212 offset:25088
	ds_read_b64_tr_b16 v[154:155], v212 offset:29184
	s_waitcnt lgkmcnt(6)
	v_mfma_f32_32x32x16_bf16 v[114:129], v[132:135], v[140:143], v[114:129]
	s_waitcnt lgkmcnt(4)
	v_mfma_f32_32x32x16_bf16 v[114:129], v[136:139], v[144:147], v[114:129]
	ds_read_b64_tr_b16 v[140:141], v212 offset:17408
	ds_read_b64_tr_b16 v[142:143], v212 offset:21504
	ds_read_b64_tr_b16 v[144:145], v212 offset:25600
	ds_read_b64_tr_b16 v[146:147], v212 offset:29696
	s_waitcnt lgkmcnt(6)
	v_mfma_f32_32x32x16_bf16 v[98:113], v[132:135], v[148:151], v[98:113]
	s_waitcnt lgkmcnt(4)
	v_mfma_f32_32x32x16_bf16 v[98:113], v[136:139], v[152:155], v[98:113]
	ds_read_b64_tr_b16 v[148:149], v212 offset:17920
	ds_read_b64_tr_b16 v[150:151], v212 offset:22016
	ds_read_b64_tr_b16 v[152:153], v212 offset:26112
	ds_read_b64_tr_b16 v[154:155], v212 offset:30208
	s_waitcnt lgkmcnt(6)
	v_mfma_f32_32x32x16_bf16 v[82:97], v[132:135], v[140:143], v[82:97]
	s_waitcnt lgkmcnt(4)
	v_mfma_f32_32x32x16_bf16 v[82:97], v[136:139], v[144:147], v[82:97]
	ds_read_b64_tr_b16 v[140:141], v212 offset:18432
	ds_read_b64_tr_b16 v[142:143], v212 offset:22528
	ds_read_b64_tr_b16 v[144:145], v212 offset:26624
	ds_read_b64_tr_b16 v[146:147], v212 offset:30720
	s_waitcnt lgkmcnt(6)
	v_mfma_f32_32x32x16_bf16 v[66:81], v[132:135], v[148:151], v[66:81]
	s_waitcnt lgkmcnt(4)
	v_mfma_f32_32x32x16_bf16 v[66:81], v[136:139], v[152:155], v[66:81]
	ds_read_b64_tr_b16 v[148:149], v212 offset:18944
	ds_read_b64_tr_b16 v[150:151], v212 offset:23040
	ds_read_b64_tr_b16 v[152:153], v212 offset:27136
	ds_read_b64_tr_b16 v[154:155], v212 offset:31232
	s_waitcnt lgkmcnt(6)
	v_mfma_f32_32x32x16_bf16 v[50:65], v[132:135], v[140:143], v[50:65]
	s_waitcnt lgkmcnt(4)
	v_mfma_f32_32x32x16_bf16 v[50:65], v[136:139], v[144:147], v[50:65]
	ds_read_b64_tr_b16 v[140:141], v212 offset:19456
	ds_read_b64_tr_b16 v[142:143], v212 offset:23552
	ds_read_b64_tr_b16 v[144:145], v212 offset:27648
	ds_read_b64_tr_b16 v[146:147], v212 offset:31744
	s_waitcnt lgkmcnt(6)
	v_mfma_f32_32x32x16_bf16 v[34:49], v[132:135], v[148:151], v[34:49]
	s_waitcnt lgkmcnt(4)
	v_mfma_f32_32x32x16_bf16 v[34:49], v[136:139], v[152:155], v[34:49]
	ds_read_b64_tr_b16 v[148:149], v212 offset:19968
	ds_read_b64_tr_b16 v[150:151], v212 offset:24064
	ds_read_b64_tr_b16 v[152:153], v212 offset:28160
	ds_read_b64_tr_b16 v[154:155], v212 offset:32256
	s_waitcnt lgkmcnt(6)
	v_mfma_f32_32x32x16_bf16 v[18:33], v[132:135], v[140:143], v[18:33]
	s_waitcnt lgkmcnt(4)
	v_mfma_f32_32x32x16_bf16 v[18:33], v[136:139], v[144:147], v[18:33]
	s_waitcnt lgkmcnt(2)
	v_mfma_f32_32x32x16_bf16 v[2:17], v[132:135], v[148:151], v[2:17]
	s_waitcnt lgkmcnt(0)
	v_mfma_f32_32x32x16_bf16 v[2:17], v[136:139], v[152:155], v[2:17]
	s_setprio 0
	s_andn2_b32 s100, s100, 0x100
	s_bitcmp1_b32 s100, 9
	s_cbranch_scc1 .LBB0_113
	s_branch .Lattn_latch2

; #define LAS __attribute__((address_space(3)))
; DI int v_rd_base(int lane) { return ((lane & 3) << 3) | (((lane >> 2) & 3) << 6) | (((lane >> 4) & 1) << 5) | (((lane >> 5) & 1) << 8); }
; #define PV_RD(D0, L0, H0, L1, H1) L0 = TRB(v_rd_off(D0, 0, 0)); H0 = TRB(v_rd_off(D0, 0, 1)); L1 = TRB(v_rd_off(D0, 1, 0)); H1 = TRB(v_rd_off(D0, 1, 1))
; #define PV_MM(D0, L0, H0, L1, H1) o[D0] = MFMA32(pa0, PK8(L0, H0), o[D0]); o[D0] = MFMA32(pa1, PK8(L1, H1), o[D0])
; #define SB() __builtin_amdgcn_sched_barrier(0)
; DI void phase_attn(int wid0, const Params& p, int L, unsigned char* lds, bool dry) {
;     ...
;                 LAS unsigned char* vbp = ldsl + 65536 + (t & 1) * 32768 + 16384 + v_rd_base(lane);
;                 __builtin_amdgcn_s_setprio(1);
;     ...
;                 {
;                     s16x4 a0, a1, a2, a3, b0_, b1_, b2_, b3_;
;                     PV_RD(0, a0, a1, a2, a3); SB();
;                     PV_RD(1, b0_, b1_, b2_, b3_); SB(); PV_MM(0, a0, a1, a2, a3); SB();
;                     PV_RD(2, a0, a1, a2, a3); SB(); PV_MM(1, b0_, b1_, b2_, b3_); SB();
;                     PV_RD(3, b0_, b1_, b2_, b3_); SB(); PV_MM(2, a0, a1, a2, a3); SB();
;                     PV_RD(4, a0, a1, a2, a3); SB(); PV_MM(3, b0_, b1_, b2_, b3_); SB();
;                     PV_RD(5, b0_, b1_, b2_, b3_); SB(); PV_MM(4, a0, a1, a2, a3); SB();
;                     PV_RD(6, a0, a1, a2, a3); SB(); PV_MM(5, b0_, b1_, b2_, b3_); SB();
;                     PV_RD(7, b0_, b1_, b2_, b3_); SB(); PV_MM(6, a0, a1, a2, a3); SB();
;                     PV_MM(7, b0_, b1_, b2_, b3_); SB();
;                 }
;     ...
;                 __builtin_amdgcn_s_setprio(0);
.Lattn_pvplain2:
	s_setprio 1
	ds_read_b64_tr_b16 v[140:141], v212 offset:32768
	ds_read_b64_tr_b16 v[142:143], v212 offset:36864
	ds_read_b64_tr_b16 v[144:145], v212 offset:40960
	ds_read_b64_tr_b16 v[146:147], v212 offset:45056
	ds_read_b64_tr_b16 v[148:149], v212 offset:33280
	ds_read_b64_tr_b16 v[150:151], v212 offset:37376
	ds_read_b64_tr_b16 v[152:153], v212 offset:41472
	ds_read_b64_tr_b16 v[154:155], v212 offset:45568
	s_waitcnt lgkmcnt(6)
	v_mfma_f32_32x32x16_bf16 v[114:129], v[156:159], v[140:143], v[114:129]
	s_waitcnt lgkmcnt(4)
	v_mfma_f32_32x32x16_bf16 v[114:129], v[160:163], v[144:147], v[114:129]
	ds_read_b64_tr_b16 v[140:141], v212 offset:33792
	ds_read_b64_tr_b16 v[142:143], v212 offset:37888
	ds_read_b64_tr_b16 v[144:145], v212 offset:41984
	ds_read_b64_tr_b16 v[146:147], v212 offset:46080
	s_waitcnt lgkmcnt(6)
	v_mfma_f32_32x32x16_bf16 v[98:113], v[156:159], v[148:151], v[98:113]
	s_waitcnt lgkmcnt(4)
	v_mfma_f32_32x32x16_bf16 v[98:113], v[160:163], v[152:155], v[98:113]
	ds_read_b64_tr_b16 v[148:149], v212 offset:34304
	ds_read_b64_tr_b16 v[150:151], v212 offset:38400
	ds_read_b64_tr_b16 v[152:153], v212 offset:42496
	ds_read_b64_tr_b16 v[154:155], v212 offset:46592
	s_waitcnt lgkmcnt(6)
	v_mfma_f32_32x32x16_bf16 v[82:97], v[156:159], v[140:143], v[82:97]
	s_waitcnt lgkmcnt(4)
	v_mfma_f32_32x32x16_bf16 v[82:97], v[160:163], v[144:147], v[82:97]
	ds_read_b64_tr_b16 v[140:141], v212 offset:34816
	ds_read_b64_tr_b16 v[142:143], v212 offset:38912
	ds_read_b64_tr_b16 v[144:145], v212 offset:43008
	ds_read_b64_tr_b16 v[146:147], v212 offset:47104
	s_waitcnt lgkmcnt(6)
	v_mfma_f32_32x32x16_bf16 v[66:81], v[156:159], v[148:151], v[66:81]
	s_waitcnt lgkmcnt(4)
	v_mfma_f32_32x32x16_bf16 v[66:81], v[160:163], v[152:155], v[66:81]
	ds_read_b64_tr_b16 v[148:149], v212 offset:35328
	ds_read_b64_tr_b16 v[150:151], v212 offset:39424
	ds_read_b64_tr_b16 v[152:153], v212 offset:43520
	ds_read_b64_tr_b16 v[154:155], v212 offset:47616
	s_waitcnt lgkmcnt(6)
	v_mfma_f32_32x32x16_bf16 v[50:65], v[156:159], v[140:143], v[50:65]
	s_waitcnt lgkmcnt(4)
	v_mfma_f32_32x32x16_bf16 v[50:65], v[160:163], v[144:147], v[50:65]
	ds_read_b64_tr_b16 v[140:141], v212 offset:35840
	ds_read_b64_tr_b16 v[142:143], v212 offset:39936
	ds_read_b64_tr_b16 v[144:145], v212 offset:44032
	ds_read_b64_tr_b16 v[146:147], v212 offset:48128
	s_waitcnt lgkmcnt(6)
	v_mfma_f32_32x32x16_bf16 v[34:49], v[156:159], v[148:151], v[34:49]
	s_waitcnt lgkmcnt(4)
	v_mfma_f32_32x32x16_bf16 v[34:49], v[160:163], v[152:155], v[34:49]
	ds_read_b64_tr_b16 v[148:149], v212 offset:36352
	ds_read_b64_tr_b16 v[150:151], v212 offset:40448
	ds_read_b64_tr_b16 v[152:153], v212 offset:44544
	ds_read_b64_tr_b16 v[154:155], v212 offset:48640
	s_waitcnt lgkmcnt(6)
	v_mfma_f32_32x32x16_bf16 v[18:33], v[156:159], v[140:143], v[18:33]
	s_waitcnt lgkmcnt(4)
	v_mfma_f32_32x32x16_bf16 v[18:33], v[160:163], v[144:147], v[18:33]
	s_waitcnt lgkmcnt(2)
	v_mfma_f32_32x32x16_bf16 v[2:17], v[156:159], v[148:151], v[2:17]
	s_waitcnt lgkmcnt(0)
	v_mfma_f32_32x32x16_bf16 v[2:17], v[160:163], v[152:155], v[2:17]
	s_setprio 0
	s_andn2_b32 s100, s100, 0x100
	s_bitcmp1_b32 s100, 9
	s_cbranch_scc1 .LBB0_113
	s_branch .Lattn_latch3
